# MLA Q and K/V up-projection GEMMs moved from the compiler-generated 128x128 register-staged loop into the hand-written shared GEMM routine (256x128 tiles, LDS-DMA), with hand-written rope / K-row / V-
# speedup vs baseline: 1.3066x; 1.0169x over previous
; DI unsigned xb_add(unsigned* p, unsigned v) { return __hip_atomic_fetch_add(p, v, __ATOMIC_RELAXED, __HIP_MEMORY_SCOPE_AGENT); }
; DI void phase_mix_a(const Params& p, int layer, char* smem) {
;     ...
;   const int MT = NTOK / 128;
;   gemm_phase<EPI_QUP>(p, layer, (const bf16_t*)(p.ws + OFF_MQN), 256, wl + W_UQ, 256, 256, (layer == 0) ? MT : NLAT / 128, 5, smem);
;   gemm_phase<EPI_KVUP>(p, layer, (const bf16_t*)(p.ws + OFF_MKVN), 128, wl + W_UKV, 128, 128, MT, 6, smem, true);
; DI void xcd_barrier(const XcdBarrier& b) {
;   asm volatile("s_waitcnt vmcnt(0)" ::: "memory");
;   __syncthreads();
;   if (threadIdx.x == 0) {
;     unsigned* bar = b.bar;
;     __builtin_amdgcn_s_waitcnt(0);
;     unsigned nloc = b.st[0], nx = b.st[1];
;     if (nloc == 0u) { xcd_barrier_complete(bar, b.x, nloc, nx); b.st[0] = nloc; b.st[1] = nx; }
;     const unsigned old = xb_add(&bar[XB_XSUB(b.x)], 1u);
;     const unsigned gen = old / nloc;
;     if (old + 1u == (gen + 1u) * nloc) {
.LBB0_599:
	v_readlane_b32 s80, v234, 34
	v_readlane_b32 s82, v234, 36
	v_readlane_b32 s84, v234, 38
	v_readlane_b32 s86, v234, 40
	v_readlane_b32 s88, v234, 42
	v_readlane_b32 s76, v234, 44
	v_readlane_b32 s53, v234, 29
	v_readlane_b32 s54, v234, 30
	v_readlane_b32 s34, v234, 31
	v_readlane_b32 s35, v234, 32
	v_readlane_b32 s14, v234, 33
	v_readlane_b32 s81, v234, 35
	v_readlane_b32 s83, v234, 37
	v_readlane_b32 s85, v234, 39
	v_readlane_b32 s87, v234, 41
	v_readlane_b32 s89, v234, 43
	v_readlane_b32 s77, v234, 45
	s_nop 3
	s_mov_b32 s100, 4
	s_branch .Lmg_entry
.LBB0_1397:
	v_mov_b32_e32 v0, v143
	s_waitcnt vmcnt(0)
	s_waitcnt vmcnt(63) expcnt(7) lgkmcnt(15)
	s_barrier
	s_mov_b64 s[0:1], exec
	v_readlane_b32 s6, v236, 2
	v_readlane_b32 s7, v236, 3
	s_and_b64 s[6:7], s[0:1], s[6:7]
	s_mov_b64 exec, s[6:7]
	s_cbranch_execz .LBB0_1445
	s_waitcnt vmcnt(0) expcnt(0) lgkmcnt(0)
	ds_read_b32 v2, v188
	ds_read_b32 v0, v189
	s_waitcnt lgkmcnt(1)
	v_cmp_ne_u32_e32 vcc, 0, v2
	s_cbranch_vccnz .LBB0_1413
	s_mov_b32 s28, 1
	s_branch .LBB0_1401

; template <int EPI>
; DI void gemm_phase(const Params& p, int layer, const bf16_t* __restrict__ A, int lda, const bf16_t* __restrict__ Bt, int ldb, int K, int MT, int NT,
;                    char* smem, bool rev = false) {
;     ...
;   int t = rev ? (int)(gridDim.x - 1 - blockIdx.x) : (int)blockIdx.x;
; DI void phase_mix_a(const Params& p, int layer, char* smem) {
;     ...
;   gemm_phase<EPI_QUP>(p, layer, (const bf16_t*)(p.ws + OFF_MQN), 256, wl + W_UQ, 256, 256, (layer == 0) ? MT : NLAT / 128, 5, smem);
;   gemm_phase<EPI_KVUP>(p, layer, (const bf16_t*)(p.ws + OFF_MKVN), 128, wl + W_UKV, 128, 128, MT, 6, smem, true);
.Lmg_reenter:
	s_mov_b32 s52, s100
	v_readlane_b32 s53, v255, 3
	s_nop 3
	v_and_b32_e32 v140, 63, v143
	v_lshrrev_b32_e32 v184, 6, v143
	v_and_b32_e32 v227, 31, v143
	v_bfe_u32 v228, v143, 5, 1
	v_readfirstlane_b32 s77, v184
	s_nop 3
	s_lshr_b32 s78, s77, 1
	s_and_b32 s79, s77, 1
	s_mul_i32 s80, s77, 0x1800
	v_readlane_b32 s66, v255, 0
	s_mov_b32 s65, s26
	s_cmp_eq_u32 s52, 5
	s_cbranch_scc0 .Lmg_norev_1
	s_and_b32 s0, s66, 7
	s_lshr_b32 s1, s66, 3
	s_lshr_b32 s10, s65, 3
	s_sub_u32 s10, s10, 1
	s_sub_u32 s1, s10, s1
	s_lshl_b32 s1, s1, 3
	s_add_u32 s66, s0, s1
.Lmg_norev_1:
	s_mul_i32 s0, s53, 0x16c0000
	s_add_u32 s0, s0, 0x1a580000
	s_add_u32 s56, s24, s0
	s_addc_u32 s57, s25, 0
	s_mov_b32 s61, 17
	s_mov_b32 s63, 3856
	s_cmp_eq_u32 s52, 0
	s_cbranch_scc1 .Lmg_mt_2
	s_cmp_eq_u32 s52, 5
	s_cbranch_scc1 .Lmg_mt_2
	s_cmp_eq_u32 s53, 0
	s_cbranch_scc1 .Lmg_mt_2
	s_mov_b32 s61, 16
	s_mov_b32 s63, 4096
.Lmg_mt_2:
	s_cmp_eq_u32 s52, 1
	s_cbranch_scc1 .Lmg_par_4
	s_cmp_eq_u32 s52, 2
	s_cbranch_scc1 .Lmg_par_5
	s_cmp_eq_u32 s52, 3
	s_cbranch_scc1 .Lmg_par_6
	s_cmp_eq_u32 s52, 4
	s_cbranch_scc1 .Lmg_par_7
	s_cmp_eq_u32 s52, 5
	s_cbranch_scc1 .Lmg_par_8

; DI void phase_mix_a(const Params& p, int layer, char* smem) {
;     ...
;   gemm_phase<EPI_QUP>(p, layer, (const bf16_t*)(p.ws + OFF_MQN), 256, wl + W_UQ, 256, 256, (layer == 0) ? MT : NLAT / 128, 5, smem);
;   gemm_phase<EPI_KVUP>(p, layer, (const bf16_t*)(p.ws + OFF_MKVN), 128, wl + W_UKV, 128, 128, MT, 6, smem, true);
.Lmg_par_6:
	s_mov_b32 s54, s24
	s_mov_b32 s55, s25
	s_movk_i32 s58, 0x40
	s_movk_i32 s59, 0x40
	s_mov_b32 s81, 0x220000
	s_mov_b32 s48, 0x10000
	s_movk_i32 s60, 88
	s_movk_i32 s62, 8
	s_movk_i32 s69, 8192
	s_add_u32 s56, s56, 0x10c0000
	s_addc_u32 s57, s57, 0
	s_branch .Lmg_pare_9
.Lmg_par_7:
	s_add_u32 s54, s24, 0x11000000
	s_addc_u32 s55, s25, 0
	s_movk_i32 s58, 0x200
	s_movk_i32 s59, 0x200
	s_mov_b32 s81, 0x40
	s_mov_b32 s48, 0x40
	s_movk_i32 s60, 8
	s_movk_i32 s62, 5
	s_movk_i32 s69, 13108
	s_add_u32 s56, s56, 0x1640000
	s_addc_u32 s57, s57, 0
	s_branch .Lmg_pare_9
.Lmg_par_8:
	s_add_u32 s54, s24, 0x12100000
	s_addc_u32 s55, s25, 0
	s_movk_i32 s58, 0x100
	s_movk_i32 s59, 0x100
	s_mov_b32 s81, 0x40
	s_mov_b32 s48, 0x40
	s_movk_i32 s60, 4
	s_movk_i32 s62, 6
	s_movk_i32 s69, 10923
	s_add_u32 s56, s56, 0x1690000
	s_addc_u32 s57, s57, 0

; DI unsigned pack2(float lo, float hi) { f32x2_t v = {lo, hi}; bf16x2_t r = __builtin_convertvector(v, bf16x2_t); return __builtin_bit_cast(unsigned, r); }
; template <int EPI>
; DI void epilogue(const Params& p, int layer, f32x16 (&acc)[2][2], int mrow0, int ncol0, int lane) {
;     ...
;   if (EPI == EPI_U) {
;     if (ncol0 < 768 && mrow0 < NLAT) {
;       bf16_t* HT = (bf16_t*)(p.ws + OFF_HT);
; #pragma unroll
;       for (int ni = 0; ni < 2; ++ni) {
;         const int col = ncol0 + ni * 32 + c, which = col >> 8, ch = col & 255;
; #pragma unroll
;         for (int mi = 0; mi < 2; ++mi)
; #pragma unroll
;           for (int g = 0; g < 4; ++g) {
;             const int row0 = mrow0 + mi * 32 + 8 * g + 4 * h, bq = row0 >> 12, s0 = row0 & 4095;
;             uint2 w;
;             w.x = pack2(acc[mi][ni][4 * g], acc[mi][ni][4 * g + 1]);
;             w.y = pack2(acc[mi][ni][4 * g + 2], acc[mi][ni][4 * g + 3]);
;             *(uint2*)(HT + (((size_t)which * NB + bq) * 256 + ch) * SEQ + s0) = w;
.Lmg_dbg_epi:
	s_nop 15
	s_nop 3
	s_cmp_eq_u32 s52, 1
	s_cbranch_scc1 .Lmg_epi1
	s_cmp_eq_u32 s52, 2
	s_cbranch_scc1 .Lmg_epi2
	s_cmp_eq_u32 s52, 3
	s_cbranch_scc1 .Lmg_epi3
	s_cmp_eq_u32 s52, 4
	s_cbranch_scc1 .Lmg_epi4
	s_cmp_eq_u32 s52, 5
	s_cbranch_scc1 .Lmg_epi5
	s_lshl_b32 s90, s78, 7
	s_add_u32 s90, s90, s67
	s_lshl_b32 s91, s79, 6
	s_add_u32 s91, s91, s68
	s_cmp_lt_u32 s91, 768
	s_cbranch_scc0 .Lmg_uvgt_12
	s_cmp_lt_u32 s67, 0x8000
	s_cbranch_scc0 .Lmg_uplain_11
	s_lshr_b32 s0, s91, 8
	s_lshl_b32 s0, s0, 3
	s_lshr_b32 s1, s67, 12
	s_add_u32 s0, s0, s1
	s_lshl_b32 s0, s0, 21
	s_add_u32 s0, s0, 0x12980000
	s_add_u32 s82, s24, s0
	s_addc_u32 s83, s25, 0
	s_and_b32 s10, s91, 255
	s_and_b32 s11, s67, 0xfff
	s_lshl_b32 s12, s78, 7
	s_add_u32 s11, s11, s12
	s_movk_i32 s13, 0x2000
	s_branch .Lmg_utr_13

; DI bf16_t f2bf(float x) { return (bf16_t)(pack2(x, x) & 0xffffu); }
; DI int crow(int reg, int h) { return (reg & 3) + 8 * (reg >> 2) + 4 * h; }
; template <int EPI>
; DI void epilogue(const Params& p, int layer, f32x16 (&acc)[2][2], int mrow0, int ncol0, int lane) {
;     ...
;   } else if (EPI == EPI_QUP) {
;     bf16_t* Qm = (bf16_t*)(p.ws + OFF_QM);
;     const float2* csm = (const float2*)(p.ws + OFF_ROPEM);
;     const float qs = 0.10206207261596577f * LOG2E;
;     const bool lat = mrow0 < NLAT;
;     float2 cst[2][16];
; #pragma unroll
;     for (int mi = 0; mi < 2; ++mi)
; #pragma unroll
;       for (int r = 0; r < 16; ++r) {
;         const int sq = (mrow0 + mi * 32 + crow(r, h)) & 4095;
;         const int pos = (c >> 4) ? (sq & 63) : (sq >> 6);
;         cst[mi][r] = lat ? csm[pos * 8 + (c & 7)] : make_float2(1.f, 0.f);
;       }
; #pragma unroll
;     for (int ni = 0; ni < 2; ++ni) {
;       int cg0 = ncol0 + ni * 32;
;       if (cg0 >= 576) continue;
;       int head = cg0 / 96, part = (cg0 % 96) >> 5;
; #pragma unroll
;       for (int mi = 0; mi < 2; ++mi)
; #pragma unroll
;         for (int r = 0; r < 16; ++r) {
;           int row = mrow0 + mi * 32 + crow(r, h);
;           int b, kp; row_info(row, b, kp);
;           float v = acc[mi][ni][r];
;           if (part == 2) {
;             float pv = __shfl_xor(v, 8);
;             if (lat) {
;               const float2 cs = cst[mi][r];
;               v = v * cs.x + ((c & 8) ? pv : -pv) * cs.y;
;             }
;           }
;           Qm[((size_t)(b * 6 + head) * NKEY + kp) * 96 + part * 32 + c] = f2bf(v * qs);
;         }
;     }
.Lmg_epi4:
	s_lshl_b32 s90, s78, 7
	s_add_u32 s90, s90, s67
	s_lshl_b32 s91, s79, 6
	s_add_u32 s91, s91, s68
	s_cmp_lt_u32 s67, 0x8000
	s_cbranch_scc0 .Lmg_bctx_20
	s_lshr_b32 s0, s67, 12
	s_and_b32 s1, s67, 0xfff
	s_add_u32 s1, s1, 256
	s_branch .Lmg_bj_21
.Lmg_bctx_20:
	s_sub_u32 s0, s67, 0x8000
	s_lshr_b32 s0, s0, 8
	s_mov_b32 s1, 0
.Lmg_bj_21:
	s_lshl_b32 s10, s78, 7
	s_add_u32 s1, s1, s10
	v_lshlrev_b32_e32 v229, 1, v227
	s_movk_i32 s10, 768
	v_mad_u32_u24 v229, v228, s10, v229
	s_lshr_b32 s28, s91, 5
	s_cmp_ge_u32 s28, 18
	s_cbranch_scc1 .Lmg_qskip_22
	s_mul_i32 s29, s28, 43
	s_lshr_b32 s29, s29, 7
	s_mul_i32 s44, s29, 3
	s_sub_u32 s44, s28, s44
	s_mul_i32 s10, s0, 6
	s_add_u32 s10, s10, s29
	s_mul_i32 s10, s10, 4352
	s_add_u32 s10, s10, s1
	s_mul_i32 s10, s10, 192
	s_lshl_b32 s11, s44, 6
	s_add_u32 s10, s10, s11
	s_add_u32 s10, s10, 0xaa00000
	s_add_u32 s82, s24, s10
	s_addc_u32 s83, s25, 0
	s_cmp_eq_u32 s44, 2
	s_cbranch_scc0 .Lmg_qrows_23
	s_cmp_lt_u32 s67, 0x8000
	s_cbranch_scc0 .Lmg_qrows_23
	v_lshrrev_b32_e32 v184, 4, v227
	v_lshlrev_b32_e32 v176, 6, v184
	v_sub_u32_e32 v185, 1, v184
	v_lshlrev_b32_e32 v177, 6, v185
	v_and_b32_e32 v186, 8, v227
	v_sub_u32_e32 v186, 8, v186
	v_lshlrev_b32_e32 v179, 28, v186
	v_mov_b32_e32 v180, 0x3e16c740
	v_and_b32_e32 v178, 7, v227
	v_lshlrev_b32_e32 v178, 3, v178
	v_lshlrev_b32_e32 v187, 2, v228
	v_mad_u32_u24 v178, v176, v187, v178
	s_and_b32 s12, s67, 0xfff
	s_lshr_b32 s12, s12, 6
	s_lshl_b32 s13, s78, 1
	s_add_u32 s12, s12, s13
	v_mov_b32_e32 v187, s12
	v_mad_u32_u24 v178, v177, v187, v178
	s_add_u32 s84, s24, 0x1e8d6000
	s_addc_u32 s85, s25, 0
	v_mad_u32_u24 v182, v176, 0, v178
	v_mad_u32_u24 v182, v177, 0, v182
	v_mad_u32_u24 v181, v176, 0, v182
	global_load_dwordx2 v[144:145], v181, s[84:85]
	v_mad_u32_u24 v181, v176, 1, v182
	global_load_dwordx2 v[146:147], v181, s[84:85]
	v_mad_u32_u24 v181, v176, 2, v182
	global_load_dwordx2 v[148:149], v181, s[84:85]
	v_mad_u32_u24 v181, v176, 3, v182
	global_load_dwordx2 v[150:151], v181, s[84:85]
	v_mad_u32_u24 v181, v176, 8, v182
	global_load_dwordx2 v[152:153], v181, s[84:85]
	v_mad_u32_u24 v181, v176, 9, v182
	global_load_dwordx2 v[154:155], v181, s[84:85]
	v_mad_u32_u24 v181, v176, 10, v182
	global_load_dwordx2 v[156:157], v181, s[84:85]
	v_mad_u32_u24 v181, v176, 11, v182
	global_load_dwordx2 v[158:159], v181, s[84:85]
	v_mad_u32_u24 v182, v176, 0, v178
	v_mad_u32_u24 v182, v177, 0, v182
	v_mad_u32_u24 v181, v176, 16, v182
	global_load_dwordx2 v[160:161], v181, s[84:85]
	v_mad_u32_u24 v181, v176, 17, v182
	global_load_dwordx2 v[162:163], v181, s[84:85]
	v_mad_u32_u24 v181, v176, 18, v182
	global_load_dwordx2 v[164:165], v181, s[84:85]
	v_mad_u32_u24 v181, v176, 19, v182
	global_load_dwordx2 v[166:167], v181, s[84:85]
	v_mad_u32_u24 v181, v176, 24, v182
	global_load_dwordx2 v[168:169], v181, s[84:85]
	v_mad_u32_u24 v181, v176, 25, v182
	global_load_dwordx2 v[170:171], v181, s[84:85]
	v_mad_u32_u24 v181, v176, 26, v182
	global_load_dwordx2 v[172:173], v181, s[84:85]
	v_mad_u32_u24 v181, v176, 27, v182
	global_load_dwordx2 v[174:175], v181, s[84:85]
	s_waitcnt vmcnt(15)
	v_mov_b32_dpp v237, v0 row_ror:8 row_mask:0xf bank_mask:0xf
	v_mul_f32_e32 v183, v0, v144
	v_xor_b32_e32 v237, v179, v237
	v_fmac_f32_e32 v183, v237, v145
	v_mul_f32_e32 v237, v180, v183
	s_waitcnt vmcnt(14)
	v_mov_b32_dpp v238, v1 row_ror:8 row_mask:0xf bank_mask:0xf
	v_mul_f32_e32 v183, v1, v146
	v_xor_b32_e32 v238, v179, v238
	v_fmac_f32_e32 v183, v238, v147
	v_mul_f32_e32 v238, v180, v183
	s_waitcnt vmcnt(13)
	v_mov_b32_dpp v239, v2 row_ror:8 row_mask:0xf bank_mask:0xf
	v_mul_f32_e32 v183, v2, v148
	v_xor_b32_e32 v239, v179, v239
	v_fmac_f32_e32 v183, v239, v149
	v_mul_f32_e32 v239, v180, v183
	s_waitcnt vmcnt(12)
	v_mov_b32_dpp v240, v3 row_ror:8 row_mask:0xf bank_mask:0xf
	v_mul_f32_e32 v183, v3, v150
	v_xor_b32_e32 v240, v179, v240
	v_fmac_f32_e32 v183, v240, v151
	v_mul_f32_e32 v240, v180, v183
	v_cvt_pk_bf16_f32 v241, v237, v238
	v_cvt_pk_bf16_f32 v242, v239, v240
	global_store_short v229, v241, s[82:83]
	global_store_short_d16_hi v229, v241, s[82:83] offset:192
	global_store_short v229, v242, s[82:83] offset:384
	global_store_short_d16_hi v229, v242, s[82:83] offset:576
	s_add_u32 s82, s82, 1536
	s_addc_u32 s83, s83, 0
	s_waitcnt vmcnt(15)
	v_mov_b32_dpp v237, v4 row_ror:8 row_mask:0xf bank_mask:0xf
	v_mul_f32_e32 v183, v4, v152
	v_xor_b32_e32 v237, v179, v237
	v_fmac_f32_e32 v183, v237, v153
	v_mul_f32_e32 v237, v180, v183
	s_waitcnt vmcnt(14)
	v_mov_b32_dpp v238, v5 row_ror:8 row_mask:0xf bank_mask:0xf
	v_mul_f32_e32 v183, v5, v154
	v_xor_b32_e32 v238, v179, v238
	v_fmac_f32_e32 v183, v238, v155
	v_mul_f32_e32 v238, v180, v183
	s_waitcnt vmcnt(13)
	v_mov_b32_dpp v239, v6 row_ror:8 row_mask:0xf bank_mask:0xf
	v_mul_f32_e32 v183, v6, v156
	v_xor_b32_e32 v239, v179, v239
	v_fmac_f32_e32 v183, v239, v157
	v_mul_f32_e32 v239, v180, v183
	s_waitcnt vmcnt(12)
	v_mov_b32_dpp v240, v7 row_ror:8 row_mask:0xf bank_mask:0xf
	v_mul_f32_e32 v183, v7, v158
	v_xor_b32_e32 v240, v179, v240
	v_fmac_f32_e32 v183, v240, v159
	v_mul_f32_e32 v240, v180, v183
	v_cvt_pk_bf16_f32 v241, v237, v238
	v_cvt_pk_bf16_f32 v242, v239, v240
	global_store_short v229, v241, s[82:83]
	global_store_short_d16_hi v229, v241, s[82:83] offset:192
	global_store_short v229, v242, s[82:83] offset:384
	global_store_short_d16_hi v229, v242, s[82:83] offset:576
	s_add_u32 s82, s82, 1536
	s_addc_u32 s83, s83, 0
	v_mad_u32_u24 v182, v176, 32, v178
	v_mad_u32_u24 v182, v177, 0, v182
	v_mad_u32_u24 v181, v176, 0, v182
	global_load_dwordx2 v[144:145], v181, s[84:85]
	v_mad_u32_u24 v181, v176, 1, v182
	global_load_dwordx2 v[146:147], v181, s[84:85]
	v_mad_u32_u24 v181, v176, 2, v182
	global_load_dwordx2 v[148:149], v181, s[84:85]
	v_mad_u32_u24 v181, v176, 3, v182
	global_load_dwordx2 v[150:151], v181, s[84:85]
	v_mad_u32_u24 v181, v176, 8, v182
	global_load_dwordx2 v[152:153], v181, s[84:85]
	v_mad_u32_u24 v181, v176, 9, v182
	global_load_dwordx2 v[154:155], v181, s[84:85]
	v_mad_u32_u24 v181, v176, 10, v182
	global_load_dwordx2 v[156:157], v181, s[84:85]
	v_mad_u32_u24 v181, v176, 11, v182
	global_load_dwordx2 v[158:159], v181, s[84:85]
	s_waitcnt vmcnt(23)
; DI bf16_t f2bf(float x) { return (bf16_t)(pack2(x, x) & 0xffffu); }
; DI int crow(int reg, int h) { return (reg & 3) + 8 * (reg >> 2) + 4 * h; }
; template <int EPI>
; DI void epilogue(const Params& p, int layer, f32x16 (&acc)[2][2], int mrow0, int ncol0, int lane) {
;     ...
;   } else if (EPI == EPI_QUP) {
;     bf16_t* Qm = (bf16_t*)(p.ws + OFF_QM);
;     const float2* csm = (const float2*)(p.ws + OFF_ROPEM);
;     const float qs = 0.10206207261596577f * LOG2E;
;     const bool lat = mrow0 < NLAT;
;     float2 cst[2][16];
; #pragma unroll
;     for (int mi = 0; mi < 2; ++mi)
; #pragma unroll
;       for (int r = 0; r < 16; ++r) {
;         const int sq = (mrow0 + mi * 32 + crow(r, h)) & 4095;
;         const int pos = (c >> 4) ? (sq & 63) : (sq >> 6);
;         cst[mi][r] = lat ? csm[pos * 8 + (c & 7)] : make_float2(1.f, 0.f);
;       }
; #pragma unroll
;     for (int ni = 0; ni < 2; ++ni) {
;       int cg0 = ncol0 + ni * 32;
;       if (cg0 >= 576) continue;
;       int head = cg0 / 96, part = (cg0 % 96) >> 5;
; #pragma unroll
;       for (int mi = 0; mi < 2; ++mi)
; #pragma unroll
;         for (int r = 0; r < 16; ++r) {
;           int row = mrow0 + mi * 32 + crow(r, h);
;           int b, kp; row_info(row, b, kp);
;           float v = acc[mi][ni][r];
;           if (part == 2) {
;             float pv = __shfl_xor(v, 8);
;             if (lat) {
;               const float2 cs = cst[mi][r];
;               v = v * cs.x + ((c & 8) ? pv : -pv) * cs.y;
;             }
;           }
;           Qm[((size_t)(b * 6 + head) * NKEY + kp) * 96 + part * 32 + c] = f2bf(v * qs);
;         }
;     }
	v_mov_b32_dpp v237, v8 row_ror:8 row_mask:0xf bank_mask:0xf
	v_mul_f32_e32 v183, v8, v160
	v_xor_b32_e32 v237, v179, v237
	v_fmac_f32_e32 v183, v237, v161
	v_mul_f32_e32 v237, v180, v183
	s_waitcnt vmcnt(22)
	v_mov_b32_dpp v238, v9 row_ror:8 row_mask:0xf bank_mask:0xf
	v_mul_f32_e32 v183, v9, v162
	v_xor_b32_e32 v238, v179, v238
	v_fmac_f32_e32 v183, v238, v163
	v_mul_f32_e32 v238, v180, v183
	s_waitcnt vmcnt(21)
	v_mov_b32_dpp v239, v10 row_ror:8 row_mask:0xf bank_mask:0xf
	v_mul_f32_e32 v183, v10, v164
	v_xor_b32_e32 v239, v179, v239
	v_fmac_f32_e32 v183, v239, v165
	v_mul_f32_e32 v239, v180, v183
	s_waitcnt vmcnt(20)
	v_mov_b32_dpp v240, v11 row_ror:8 row_mask:0xf bank_mask:0xf
	v_mul_f32_e32 v183, v11, v166
	v_xor_b32_e32 v240, v179, v240
	v_fmac_f32_e32 v183, v240, v167
	v_mul_f32_e32 v240, v180, v183
	v_cvt_pk_bf16_f32 v241, v237, v238
	v_cvt_pk_bf16_f32 v242, v239, v240
	global_store_short v229, v241, s[82:83]
	global_store_short_d16_hi v229, v241, s[82:83] offset:192
	global_store_short v229, v242, s[82:83] offset:384
	global_store_short_d16_hi v229, v242, s[82:83] offset:576
	s_add_u32 s82, s82, 1536
	s_addc_u32 s83, s83, 0
	s_waitcnt vmcnt(23)
	v_mov_b32_dpp v237, v12 row_ror:8 row_mask:0xf bank_mask:0xf
	v_mul_f32_e32 v183, v12, v168
	v_xor_b32_e32 v237, v179, v237
	v_fmac_f32_e32 v183, v237, v169
	v_mul_f32_e32 v237, v180, v183
	s_waitcnt vmcnt(22)
	v_mov_b32_dpp v238, v13 row_ror:8 row_mask:0xf bank_mask:0xf
	v_mul_f32_e32 v183, v13, v170
	v_xor_b32_e32 v238, v179, v238
	v_fmac_f32_e32 v183, v238, v171
	v_mul_f32_e32 v238, v180, v183
	s_waitcnt vmcnt(21)
	v_mov_b32_dpp v239, v14 row_ror:8 row_mask:0xf bank_mask:0xf
	v_mul_f32_e32 v183, v14, v172
	v_xor_b32_e32 v239, v179, v239
	v_fmac_f32_e32 v183, v239, v173
	v_mul_f32_e32 v239, v180, v183
	s_waitcnt vmcnt(20)
	v_mov_b32_dpp v240, v15 row_ror:8 row_mask:0xf bank_mask:0xf
	v_mul_f32_e32 v183, v15, v174
	v_xor_b32_e32 v240, v179, v240
	v_fmac_f32_e32 v183, v240, v175
	v_mul_f32_e32 v240, v180, v183
	v_cvt_pk_bf16_f32 v241, v237, v238
	v_cvt_pk_bf16_f32 v242, v239, v240
	global_store_short v229, v241, s[82:83]
	global_store_short_d16_hi v229, v241, s[82:83] offset:192
	global_store_short v229, v242, s[82:83] offset:384
	global_store_short_d16_hi v229, v242, s[82:83] offset:576
	s_add_u32 s82, s82, 1536
	s_addc_u32 s83, s83, 0
	v_mad_u32_u24 v182, v176, 32, v178
	v_mad_u32_u24 v182, v177, 0, v182
	v_mad_u32_u24 v181, v176, 16, v182
	global_load_dwordx2 v[160:161], v181, s[84:85]
	v_mad_u32_u24 v181, v176, 17, v182
	global_load_dwordx2 v[162:163], v181, s[84:85]
	v_mad_u32_u24 v181, v176, 18, v182
	global_load_dwordx2 v[164:165], v181, s[84:85]
	v_mad_u32_u24 v181, v176, 19, v182
	global_load_dwordx2 v[166:167], v181, s[84:85]
	v_mad_u32_u24 v181, v176, 24, v182
	global_load_dwordx2 v[168:169], v181, s[84:85]
	v_mad_u32_u24 v181, v176, 25, v182
	global_load_dwordx2 v[170:171], v181, s[84:85]
	v_mad_u32_u24 v181, v176, 26, v182
	global_load_dwordx2 v[172:173], v181, s[84:85]
	v_mad_u32_u24 v181, v176, 27, v182
	global_load_dwordx2 v[174:175], v181, s[84:85]
	s_waitcnt vmcnt(23)
	v_mov_b32_dpp v237, v32 row_ror:8 row_mask:0xf bank_mask:0xf
	v_mul_f32_e32 v183, v32, v144
	v_xor_b32_e32 v237, v179, v237
	v_fmac_f32_e32 v183, v237, v145
	v_mul_f32_e32 v237, v180, v183
	s_waitcnt vmcnt(22)
	v_mov_b32_dpp v238, v33 row_ror:8 row_mask:0xf bank_mask:0xf
	v_mul_f32_e32 v183, v33, v146
	v_xor_b32_e32 v238, v179, v238
	v_fmac_f32_e32 v183, v238, v147
	v_mul_f32_e32 v238, v180, v183
	s_waitcnt vmcnt(21)
	v_mov_b32_dpp v239, v34 row_ror:8 row_mask:0xf bank_mask:0xf
	v_mul_f32_e32 v183, v34, v148
	v_xor_b32_e32 v239, v179, v239
	v_fmac_f32_e32 v183, v239, v149
	v_mul_f32_e32 v239, v180, v183
	s_waitcnt vmcnt(20)
	v_mov_b32_dpp v240, v35 row_ror:8 row_mask:0xf bank_mask:0xf
	v_mul_f32_e32 v183, v35, v150
	v_xor_b32_e32 v240, v179, v240
	v_fmac_f32_e32 v183, v240, v151
	v_mul_f32_e32 v240, v180, v183
	v_cvt_pk_bf16_f32 v241, v237, v238
	v_cvt_pk_bf16_f32 v242, v239, v240
	global_store_short v229, v241, s[82:83]
	global_store_short_d16_hi v229, v241, s[82:83] offset:192
	global_store_short v229, v242, s[82:83] offset:384
	global_store_short_d16_hi v229, v242, s[82:83] offset:576
	s_add_u32 s82, s82, 1536
	s_addc_u32 s83, s83, 0
	s_waitcnt vmcnt(23)
	v_mov_b32_dpp v237, v36 row_ror:8 row_mask:0xf bank_mask:0xf
	v_mul_f32_e32 v183, v36, v152
	v_xor_b32_e32 v237, v179, v237
	v_fmac_f32_e32 v183, v237, v153
	v_mul_f32_e32 v237, v180, v183
	s_waitcnt vmcnt(22)
	v_mov_b32_dpp v238, v37 row_ror:8 row_mask:0xf bank_mask:0xf
	v_mul_f32_e32 v183, v37, v154
	v_xor_b32_e32 v238, v179, v238
	v_fmac_f32_e32 v183, v238, v155
	v_mul_f32_e32 v238, v180, v183
	s_waitcnt vmcnt(21)
	v_mov_b32_dpp v239, v38 row_ror:8 row_mask:0xf bank_mask:0xf
	v_mul_f32_e32 v183, v38, v156
	v_xor_b32_e32 v239, v179, v239
	v_fmac_f32_e32 v183, v239, v157
	v_mul_f32_e32 v239, v180, v183
	s_waitcnt vmcnt(20)
	v_mov_b32_dpp v240, v39 row_ror:8 row_mask:0xf bank_mask:0xf
	v_mul_f32_e32 v183, v39, v158
	v_xor_b32_e32 v240, v179, v240
	v_fmac_f32_e32 v183, v240, v159
	v_mul_f32_e32 v240, v180, v183
	v_cvt_pk_bf16_f32 v241, v237, v238
	v_cvt_pk_bf16_f32 v242, v239, v240
	global_store_short v229, v241, s[82:83]
	global_store_short_d16_hi v229, v241, s[82:83] offset:192
	global_store_short v229, v242, s[82:83] offset:384
	global_store_short_d16_hi v229, v242, s[82:83] offset:576
	s_add_u32 s82, s82, 1536
	s_addc_u32 s83, s83, 0
	v_mad_u32_u24 v182, v176, 0, v178
	v_mad_u32_u24 v182, v177, 1, v182
	v_mad_u32_u24 v181, v176, 0, v182
	global_load_dwordx2 v[144:145], v181, s[84:85]
	v_mad_u32_u24 v181, v176, 1, v182
	global_load_dwordx2 v[146:147], v181, s[84:85]
	v_mad_u32_u24 v181, v176, 2, v182
	global_load_dwordx2 v[148:149], v181, s[84:85]
	v_mad_u32_u24 v181, v176, 3, v182
	global_load_dwordx2 v[150:151], v181, s[84:85]
	v_mad_u32_u24 v181, v176, 8, v182
	global_load_dwordx2 v[152:153], v181, s[84:85]
	v_mad_u32_u24 v181, v176, 9, v182
	global_load_dwordx2 v[154:155], v181, s[84:85]
	v_mad_u32_u24 v181, v176, 10, v182
	global_load_dwordx2 v[156:157], v181, s[84:85]
	v_mad_u32_u24 v181, v176, 11, v182
	global_load_dwordx2 v[158:159], v181, s[84:85]
	s_waitcnt vmcnt(23)
; DI bf16_t f2bf(float x) { return (bf16_t)(pack2(x, x) & 0xffffu); }
; DI int crow(int reg, int h) { return (reg & 3) + 8 * (reg >> 2) + 4 * h; }
; template <int EPI>
; DI void epilogue(const Params& p, int layer, f32x16 (&acc)[2][2], int mrow0, int ncol0, int lane) {
;     ...
;   } else if (EPI == EPI_QUP) {
;     bf16_t* Qm = (bf16_t*)(p.ws + OFF_QM);
;     const float2* csm = (const float2*)(p.ws + OFF_ROPEM);
;     const float qs = 0.10206207261596577f * LOG2E;
;     const bool lat = mrow0 < NLAT;
;     float2 cst[2][16];
; #pragma unroll
;     for (int mi = 0; mi < 2; ++mi)
; #pragma unroll
;       for (int r = 0; r < 16; ++r) {
;         const int sq = (mrow0 + mi * 32 + crow(r, h)) & 4095;
;         const int pos = (c >> 4) ? (sq & 63) : (sq >> 6);
;         cst[mi][r] = lat ? csm[pos * 8 + (c & 7)] : make_float2(1.f, 0.f);
;       }
; #pragma unroll
;     for (int ni = 0; ni < 2; ++ni) {
;       int cg0 = ncol0 + ni * 32;
;       if (cg0 >= 576) continue;
;       int head = cg0 / 96, part = (cg0 % 96) >> 5;
; #pragma unroll
;       for (int mi = 0; mi < 2; ++mi)
; #pragma unroll
;         for (int r = 0; r < 16; ++r) {
;           int row = mrow0 + mi * 32 + crow(r, h);
;           int b, kp; row_info(row, b, kp);
;           float v = acc[mi][ni][r];
;           if (part == 2) {
;             float pv = __shfl_xor(v, 8);
;             if (lat) {
;               const float2 cs = cst[mi][r];
;               v = v * cs.x + ((c & 8) ? pv : -pv) * cs.y;
;             }
;           }
;           Qm[((size_t)(b * 6 + head) * NKEY + kp) * 96 + part * 32 + c] = f2bf(v * qs);
;         }
;     }
	v_mov_b32_dpp v237, v40 row_ror:8 row_mask:0xf bank_mask:0xf
	v_mul_f32_e32 v183, v40, v160
	v_xor_b32_e32 v237, v179, v237
	v_fmac_f32_e32 v183, v237, v161
	v_mul_f32_e32 v237, v180, v183
	s_waitcnt vmcnt(22)
	v_mov_b32_dpp v238, v41 row_ror:8 row_mask:0xf bank_mask:0xf
	v_mul_f32_e32 v183, v41, v162
	v_xor_b32_e32 v238, v179, v238
	v_fmac_f32_e32 v183, v238, v163
	v_mul_f32_e32 v238, v180, v183
	s_waitcnt vmcnt(21)
	v_mov_b32_dpp v239, v42 row_ror:8 row_mask:0xf bank_mask:0xf
	v_mul_f32_e32 v183, v42, v164
	v_xor_b32_e32 v239, v179, v239
	v_fmac_f32_e32 v183, v239, v165
	v_mul_f32_e32 v239, v180, v183
	s_waitcnt vmcnt(20)
	v_mov_b32_dpp v240, v43 row_ror:8 row_mask:0xf bank_mask:0xf
	v_mul_f32_e32 v183, v43, v166
	v_xor_b32_e32 v240, v179, v240
	v_fmac_f32_e32 v183, v240, v167
	v_mul_f32_e32 v240, v180, v183
	v_cvt_pk_bf16_f32 v241, v237, v238
	v_cvt_pk_bf16_f32 v242, v239, v240
	global_store_short v229, v241, s[82:83]
	global_store_short_d16_hi v229, v241, s[82:83] offset:192
	global_store_short v229, v242, s[82:83] offset:384
	global_store_short_d16_hi v229, v242, s[82:83] offset:576
	s_add_u32 s82, s82, 1536
	s_addc_u32 s83, s83, 0
	s_waitcnt vmcnt(23)
	v_mov_b32_dpp v237, v44 row_ror:8 row_mask:0xf bank_mask:0xf
	v_mul_f32_e32 v183, v44, v168
	v_xor_b32_e32 v237, v179, v237
	v_fmac_f32_e32 v183, v237, v169
	v_mul_f32_e32 v237, v180, v183
	s_waitcnt vmcnt(22)
	v_mov_b32_dpp v238, v45 row_ror:8 row_mask:0xf bank_mask:0xf
	v_mul_f32_e32 v183, v45, v170
	v_xor_b32_e32 v238, v179, v238
	v_fmac_f32_e32 v183, v238, v171
	v_mul_f32_e32 v238, v180, v183
	s_waitcnt vmcnt(21)
	v_mov_b32_dpp v239, v46 row_ror:8 row_mask:0xf bank_mask:0xf
	v_mul_f32_e32 v183, v46, v172
	v_xor_b32_e32 v239, v179, v239
	v_fmac_f32_e32 v183, v239, v173
	v_mul_f32_e32 v239, v180, v183
	s_waitcnt vmcnt(20)
	v_mov_b32_dpp v240, v47 row_ror:8 row_mask:0xf bank_mask:0xf
	v_mul_f32_e32 v183, v47, v174
	v_xor_b32_e32 v240, v179, v240
	v_fmac_f32_e32 v183, v240, v175
	v_mul_f32_e32 v240, v180, v183
	v_cvt_pk_bf16_f32 v241, v237, v238
	v_cvt_pk_bf16_f32 v242, v239, v240
	global_store_short v229, v241, s[82:83]
	global_store_short_d16_hi v229, v241, s[82:83] offset:192
	global_store_short v229, v242, s[82:83] offset:384
	global_store_short_d16_hi v229, v242, s[82:83] offset:576
	s_add_u32 s82, s82, 1536
	s_addc_u32 s83, s83, 0
	v_mad_u32_u24 v182, v176, 0, v178
	v_mad_u32_u24 v182, v177, 1, v182
	v_mad_u32_u24 v181, v176, 16, v182
	global_load_dwordx2 v[160:161], v181, s[84:85]
	v_mad_u32_u24 v181, v176, 17, v182
	global_load_dwordx2 v[162:163], v181, s[84:85]
	v_mad_u32_u24 v181, v176, 18, v182
	global_load_dwordx2 v[164:165], v181, s[84:85]
	v_mad_u32_u24 v181, v176, 19, v182
	global_load_dwordx2 v[166:167], v181, s[84:85]
	v_mad_u32_u24 v181, v176, 24, v182
	global_load_dwordx2 v[168:169], v181, s[84:85]
	v_mad_u32_u24 v181, v176, 25, v182
	global_load_dwordx2 v[170:171], v181, s[84:85]
	v_mad_u32_u24 v181, v176, 26, v182
	global_load_dwordx2 v[172:173], v181, s[84:85]
	v_mad_u32_u24 v181, v176, 27, v182
	global_load_dwordx2 v[174:175], v181, s[84:85]
	s_waitcnt vmcnt(23)
	v_mov_b32_dpp v237, v64 row_ror:8 row_mask:0xf bank_mask:0xf
	v_mul_f32_e32 v183, v64, v144
	v_xor_b32_e32 v237, v179, v237
	v_fmac_f32_e32 v183, v237, v145
	v_mul_f32_e32 v237, v180, v183
	s_waitcnt vmcnt(22)
	v_mov_b32_dpp v238, v65 row_ror:8 row_mask:0xf bank_mask:0xf
	v_mul_f32_e32 v183, v65, v146
	v_xor_b32_e32 v238, v179, v238
	v_fmac_f32_e32 v183, v238, v147
	v_mul_f32_e32 v238, v180, v183
	s_waitcnt vmcnt(21)
	v_mov_b32_dpp v239, v66 row_ror:8 row_mask:0xf bank_mask:0xf
	v_mul_f32_e32 v183, v66, v148
	v_xor_b32_e32 v239, v179, v239
	v_fmac_f32_e32 v183, v239, v149
	v_mul_f32_e32 v239, v180, v183
	s_waitcnt vmcnt(20)
	v_mov_b32_dpp v240, v67 row_ror:8 row_mask:0xf bank_mask:0xf
	v_mul_f32_e32 v183, v67, v150
	v_xor_b32_e32 v240, v179, v240
	v_fmac_f32_e32 v183, v240, v151
	v_mul_f32_e32 v240, v180, v183
	v_cvt_pk_bf16_f32 v241, v237, v238
	v_cvt_pk_bf16_f32 v242, v239, v240
	global_store_short v229, v241, s[82:83]
	global_store_short_d16_hi v229, v241, s[82:83] offset:192
	global_store_short v229, v242, s[82:83] offset:384
	global_store_short_d16_hi v229, v242, s[82:83] offset:576
	s_add_u32 s82, s82, 1536
	s_addc_u32 s83, s83, 0
	s_waitcnt vmcnt(23)
	v_mov_b32_dpp v237, v68 row_ror:8 row_mask:0xf bank_mask:0xf
	v_mul_f32_e32 v183, v68, v152
	v_xor_b32_e32 v237, v179, v237
	v_fmac_f32_e32 v183, v237, v153
	v_mul_f32_e32 v237, v180, v183
	s_waitcnt vmcnt(22)
	v_mov_b32_dpp v238, v69 row_ror:8 row_mask:0xf bank_mask:0xf
	v_mul_f32_e32 v183, v69, v154
	v_xor_b32_e32 v238, v179, v238
	v_fmac_f32_e32 v183, v238, v155
	v_mul_f32_e32 v238, v180, v183
	s_waitcnt vmcnt(21)
	v_mov_b32_dpp v239, v70 row_ror:8 row_mask:0xf bank_mask:0xf
	v_mul_f32_e32 v183, v70, v156
	v_xor_b32_e32 v239, v179, v239
	v_fmac_f32_e32 v183, v239, v157
	v_mul_f32_e32 v239, v180, v183
	s_waitcnt vmcnt(20)
	v_mov_b32_dpp v240, v71 row_ror:8 row_mask:0xf bank_mask:0xf
	v_mul_f32_e32 v183, v71, v158
	v_xor_b32_e32 v240, v179, v240
	v_fmac_f32_e32 v183, v240, v159
	v_mul_f32_e32 v240, v180, v183
	v_cvt_pk_bf16_f32 v241, v237, v238
	v_cvt_pk_bf16_f32 v242, v239, v240
	global_store_short v229, v241, s[82:83]
	global_store_short_d16_hi v229, v241, s[82:83] offset:192
	global_store_short v229, v242, s[82:83] offset:384
	global_store_short_d16_hi v229, v242, s[82:83] offset:576
	s_add_u32 s82, s82, 1536
	s_addc_u32 s83, s83, 0
	v_mad_u32_u24 v182, v176, 32, v178
	v_mad_u32_u24 v182, v177, 1, v182
	v_mad_u32_u24 v181, v176, 0, v182
	global_load_dwordx2 v[144:145], v181, s[84:85]
	v_mad_u32_u24 v181, v176, 1, v182
	global_load_dwordx2 v[146:147], v181, s[84:85]
	v_mad_u32_u24 v181, v176, 2, v182
	global_load_dwordx2 v[148:149], v181, s[84:85]
	v_mad_u32_u24 v181, v176, 3, v182
	global_load_dwordx2 v[150:151], v181, s[84:85]
	v_mad_u32_u24 v181, v176, 8, v182
	global_load_dwordx2 v[152:153], v181, s[84:85]
	v_mad_u32_u24 v181, v176, 9, v182
	global_load_dwordx2 v[154:155], v181, s[84:85]
	v_mad_u32_u24 v181, v176, 10, v182
	global_load_dwordx2 v[156:157], v181, s[84:85]
	v_mad_u32_u24 v181, v176, 11, v182
	global_load_dwordx2 v[158:159], v181, s[84:85]
	s_waitcnt vmcnt(23)
; DI bf16_t f2bf(float x) { return (bf16_t)(pack2(x, x) & 0xffffu); }
; DI int crow(int reg, int h) { return (reg & 3) + 8 * (reg >> 2) + 4 * h; }
; template <int EPI>
; DI void epilogue(const Params& p, int layer, f32x16 (&acc)[2][2], int mrow0, int ncol0, int lane) {
;     ...
;   } else if (EPI == EPI_QUP) {
;     bf16_t* Qm = (bf16_t*)(p.ws + OFF_QM);
;     const float2* csm = (const float2*)(p.ws + OFF_ROPEM);
;     const float qs = 0.10206207261596577f * LOG2E;
;     const bool lat = mrow0 < NLAT;
;     float2 cst[2][16];
; #pragma unroll
;     for (int mi = 0; mi < 2; ++mi)
; #pragma unroll
;       for (int r = 0; r < 16; ++r) {
;         const int sq = (mrow0 + mi * 32 + crow(r, h)) & 4095;
;         const int pos = (c >> 4) ? (sq & 63) : (sq >> 6);
;         cst[mi][r] = lat ? csm[pos * 8 + (c & 7)] : make_float2(1.f, 0.f);
;       }
; #pragma unroll
;     for (int ni = 0; ni < 2; ++ni) {
;       int cg0 = ncol0 + ni * 32;
;       if (cg0 >= 576) continue;
;       int head = cg0 / 96, part = (cg0 % 96) >> 5;
; #pragma unroll
;       for (int mi = 0; mi < 2; ++mi)
; #pragma unroll
;         for (int r = 0; r < 16; ++r) {
;           int row = mrow0 + mi * 32 + crow(r, h);
;           int b, kp; row_info(row, b, kp);
;           float v = acc[mi][ni][r];
;           if (part == 2) {
;             float pv = __shfl_xor(v, 8);
;             if (lat) {
;               const float2 cs = cst[mi][r];
;               v = v * cs.x + ((c & 8) ? pv : -pv) * cs.y;
;             }
;           }
;           Qm[((size_t)(b * 6 + head) * NKEY + kp) * 96 + part * 32 + c] = f2bf(v * qs);
;         }
;     }
	v_mov_b32_dpp v237, v72 row_ror:8 row_mask:0xf bank_mask:0xf
	v_mul_f32_e32 v183, v72, v160
	v_xor_b32_e32 v237, v179, v237
	v_fmac_f32_e32 v183, v237, v161
	v_mul_f32_e32 v237, v180, v183
	s_waitcnt vmcnt(22)
	v_mov_b32_dpp v238, v73 row_ror:8 row_mask:0xf bank_mask:0xf
	v_mul_f32_e32 v183, v73, v162
	v_xor_b32_e32 v238, v179, v238
	v_fmac_f32_e32 v183, v238, v163
	v_mul_f32_e32 v238, v180, v183
	s_waitcnt vmcnt(21)
	v_mov_b32_dpp v239, v74 row_ror:8 row_mask:0xf bank_mask:0xf
	v_mul_f32_e32 v183, v74, v164
	v_xor_b32_e32 v239, v179, v239
	v_fmac_f32_e32 v183, v239, v165
	v_mul_f32_e32 v239, v180, v183
	s_waitcnt vmcnt(20)
	v_mov_b32_dpp v240, v75 row_ror:8 row_mask:0xf bank_mask:0xf
	v_mul_f32_e32 v183, v75, v166
	v_xor_b32_e32 v240, v179, v240
	v_fmac_f32_e32 v183, v240, v167
	v_mul_f32_e32 v240, v180, v183
	v_cvt_pk_bf16_f32 v241, v237, v238
	v_cvt_pk_bf16_f32 v242, v239, v240
	global_store_short v229, v241, s[82:83]
	global_store_short_d16_hi v229, v241, s[82:83] offset:192
	global_store_short v229, v242, s[82:83] offset:384
	global_store_short_d16_hi v229, v242, s[82:83] offset:576
	s_add_u32 s82, s82, 1536
	s_addc_u32 s83, s83, 0
	s_waitcnt vmcnt(23)
	v_mov_b32_dpp v237, v76 row_ror:8 row_mask:0xf bank_mask:0xf
	v_mul_f32_e32 v183, v76, v168
	v_xor_b32_e32 v237, v179, v237
	v_fmac_f32_e32 v183, v237, v169
	v_mul_f32_e32 v237, v180, v183
	s_waitcnt vmcnt(22)
	v_mov_b32_dpp v238, v77 row_ror:8 row_mask:0xf bank_mask:0xf
	v_mul_f32_e32 v183, v77, v170
	v_xor_b32_e32 v238, v179, v238
	v_fmac_f32_e32 v183, v238, v171
	v_mul_f32_e32 v238, v180, v183
	s_waitcnt vmcnt(21)
	v_mov_b32_dpp v239, v78 row_ror:8 row_mask:0xf bank_mask:0xf
	v_mul_f32_e32 v183, v78, v172
	v_xor_b32_e32 v239, v179, v239
	v_fmac_f32_e32 v183, v239, v173
	v_mul_f32_e32 v239, v180, v183
	s_waitcnt vmcnt(20)
	v_mov_b32_dpp v240, v79 row_ror:8 row_mask:0xf bank_mask:0xf
	v_mul_f32_e32 v183, v79, v174
	v_xor_b32_e32 v240, v179, v240
	v_fmac_f32_e32 v183, v240, v175
	v_mul_f32_e32 v240, v180, v183
	v_cvt_pk_bf16_f32 v241, v237, v238
	v_cvt_pk_bf16_f32 v242, v239, v240
	global_store_short v229, v241, s[82:83]
	global_store_short_d16_hi v229, v241, s[82:83] offset:192
	global_store_short v229, v242, s[82:83] offset:384
	global_store_short_d16_hi v229, v242, s[82:83] offset:576
	s_add_u32 s82, s82, 1536
	s_addc_u32 s83, s83, 0
	v_mad_u32_u24 v182, v176, 32, v178
	v_mad_u32_u24 v182, v177, 1, v182
	v_mad_u32_u24 v181, v176, 16, v182
	global_load_dwordx2 v[160:161], v181, s[84:85]
	v_mad_u32_u24 v181, v176, 17, v182
	global_load_dwordx2 v[162:163], v181, s[84:85]
	v_mad_u32_u24 v181, v176, 18, v182
	global_load_dwordx2 v[164:165], v181, s[84:85]
	v_mad_u32_u24 v181, v176, 19, v182
	global_load_dwordx2 v[166:167], v181, s[84:85]
	v_mad_u32_u24 v181, v176, 24, v182
	global_load_dwordx2 v[168:169], v181, s[84:85]
	v_mad_u32_u24 v181, v176, 25, v182
	global_load_dwordx2 v[170:171], v181, s[84:85]
	v_mad_u32_u24 v181, v176, 26, v182
	global_load_dwordx2 v[172:173], v181, s[84:85]
	v_mad_u32_u24 v181, v176, 27, v182
	global_load_dwordx2 v[174:175], v181, s[84:85]
	s_waitcnt vmcnt(23)
	v_mov_b32_dpp v237, v96 row_ror:8 row_mask:0xf bank_mask:0xf
	v_mul_f32_e32 v183, v96, v144
	v_xor_b32_e32 v237, v179, v237
	v_fmac_f32_e32 v183, v237, v145
	v_mul_f32_e32 v237, v180, v183
	s_waitcnt vmcnt(22)
	v_mov_b32_dpp v238, v97 row_ror:8 row_mask:0xf bank_mask:0xf
	v_mul_f32_e32 v183, v97, v146
	v_xor_b32_e32 v238, v179, v238
	v_fmac_f32_e32 v183, v238, v147
	v_mul_f32_e32 v238, v180, v183
	s_waitcnt vmcnt(21)
	v_mov_b32_dpp v239, v98 row_ror:8 row_mask:0xf bank_mask:0xf
	v_mul_f32_e32 v183, v98, v148
	v_xor_b32_e32 v239, v179, v239
	v_fmac_f32_e32 v183, v239, v149
	v_mul_f32_e32 v239, v180, v183
	s_waitcnt vmcnt(20)
	v_mov_b32_dpp v240, v99 row_ror:8 row_mask:0xf bank_mask:0xf
	v_mul_f32_e32 v183, v99, v150
	v_xor_b32_e32 v240, v179, v240
	v_fmac_f32_e32 v183, v240, v151
	v_mul_f32_e32 v240, v180, v183
	v_cvt_pk_bf16_f32 v241, v237, v238
	v_cvt_pk_bf16_f32 v242, v239, v240
	global_store_short v229, v241, s[82:83]
	global_store_short_d16_hi v229, v241, s[82:83] offset:192
	global_store_short v229, v242, s[82:83] offset:384
	global_store_short_d16_hi v229, v242, s[82:83] offset:576
	s_add_u32 s82, s82, 1536
	s_addc_u32 s83, s83, 0
	s_waitcnt vmcnt(23)
	v_mov_b32_dpp v237, v100 row_ror:8 row_mask:0xf bank_mask:0xf
	v_mul_f32_e32 v183, v100, v152
	v_xor_b32_e32 v237, v179, v237
	v_fmac_f32_e32 v183, v237, v153
	v_mul_f32_e32 v237, v180, v183
	s_waitcnt vmcnt(22)
	v_mov_b32_dpp v238, v101 row_ror:8 row_mask:0xf bank_mask:0xf
	v_mul_f32_e32 v183, v101, v154
	v_xor_b32_e32 v238, v179, v238
	v_fmac_f32_e32 v183, v238, v155
	v_mul_f32_e32 v238, v180, v183
	s_waitcnt vmcnt(21)
	v_mov_b32_dpp v239, v102 row_ror:8 row_mask:0xf bank_mask:0xf
	v_mul_f32_e32 v183, v102, v156
	v_xor_b32_e32 v239, v179, v239
	v_fmac_f32_e32 v183, v239, v157
	v_mul_f32_e32 v239, v180, v183
	s_waitcnt vmcnt(20)
	v_mov_b32_dpp v240, v103 row_ror:8 row_mask:0xf bank_mask:0xf
	v_mul_f32_e32 v183, v103, v158
	v_xor_b32_e32 v240, v179, v240
	v_fmac_f32_e32 v183, v240, v159
	v_mul_f32_e32 v240, v180, v183
	v_cvt_pk_bf16_f32 v241, v237, v238
	v_cvt_pk_bf16_f32 v242, v239, v240
	global_store_short v229, v241, s[82:83]
	global_store_short_d16_hi v229, v241, s[82:83] offset:192
	global_store_short v229, v242, s[82:83] offset:384
	global_store_short_d16_hi v229, v242, s[82:83] offset:576
	s_add_u32 s82, s82, 1536
	s_addc_u32 s83, s83, 0
	s_waitcnt vmcnt(15)
	v_mov_b32_dpp v237, v104 row_ror:8 row_mask:0xf bank_mask:0xf
	v_mul_f32_e32 v183, v104, v160
	v_xor_b32_e32 v237, v179, v237
	v_fmac_f32_e32 v183, v237, v161
	v_mul_f32_e32 v237, v180, v183
	s_waitcnt vmcnt(14)
; DI bf16_t f2bf(float x) { return (bf16_t)(pack2(x, x) & 0xffffu); }
; DI int crow(int reg, int h) { return (reg & 3) + 8 * (reg >> 2) + 4 * h; }
; template <int EPI>
; DI void epilogue(const Params& p, int layer, f32x16 (&acc)[2][2], int mrow0, int ncol0, int lane) {
;     ...
;   } else if (EPI == EPI_QUP) {
;     bf16_t* Qm = (bf16_t*)(p.ws + OFF_QM);
;     const float2* csm = (const float2*)(p.ws + OFF_ROPEM);
;     const float qs = 0.10206207261596577f * LOG2E;
;     const bool lat = mrow0 < NLAT;
;     float2 cst[2][16];
; #pragma unroll
;     for (int mi = 0; mi < 2; ++mi)
; #pragma unroll
;       for (int r = 0; r < 16; ++r) {
;         const int sq = (mrow0 + mi * 32 + crow(r, h)) & 4095;
;         const int pos = (c >> 4) ? (sq & 63) : (sq >> 6);
;         cst[mi][r] = lat ? csm[pos * 8 + (c & 7)] : make_float2(1.f, 0.f);
;       }
; #pragma unroll
;     for (int ni = 0; ni < 2; ++ni) {
;       int cg0 = ncol0 + ni * 32;
;       if (cg0 >= 576) continue;
;       int head = cg0 / 96, part = (cg0 % 96) >> 5;
; #pragma unroll
;       for (int mi = 0; mi < 2; ++mi)
; #pragma unroll
;         for (int r = 0; r < 16; ++r) {
;           int row = mrow0 + mi * 32 + crow(r, h);
;           int b, kp; row_info(row, b, kp);
;           float v = acc[mi][ni][r];
;           if (part == 2) {
;             float pv = __shfl_xor(v, 8);
;             if (lat) {
;               const float2 cs = cst[mi][r];
;               v = v * cs.x + ((c & 8) ? pv : -pv) * cs.y;
;             }
;           }
;           Qm[((size_t)(b * 6 + head) * NKEY + kp) * 96 + part * 32 + c] = f2bf(v * qs);
;         }
;     }
	v_mov_b32_dpp v238, v105 row_ror:8 row_mask:0xf bank_mask:0xf
	v_mul_f32_e32 v183, v105, v162
	v_xor_b32_e32 v238, v179, v238
	v_fmac_f32_e32 v183, v238, v163
	v_mul_f32_e32 v238, v180, v183
	s_waitcnt vmcnt(13)
	v_mov_b32_dpp v239, v106 row_ror:8 row_mask:0xf bank_mask:0xf
	v_mul_f32_e32 v183, v106, v164
	v_xor_b32_e32 v239, v179, v239
	v_fmac_f32_e32 v183, v239, v165
	v_mul_f32_e32 v239, v180, v183
	s_waitcnt vmcnt(12)
	v_mov_b32_dpp v240, v107 row_ror:8 row_mask:0xf bank_mask:0xf
	v_mul_f32_e32 v183, v107, v166
	v_xor_b32_e32 v240, v179, v240
	v_fmac_f32_e32 v183, v240, v167
	v_mul_f32_e32 v240, v180, v183
	v_cvt_pk_bf16_f32 v241, v237, v238
	v_cvt_pk_bf16_f32 v242, v239, v240
	global_store_short v229, v241, s[82:83]
	global_store_short_d16_hi v229, v241, s[82:83] offset:192
	global_store_short v229, v242, s[82:83] offset:384
	global_store_short_d16_hi v229, v242, s[82:83] offset:576
	s_add_u32 s82, s82, 1536
	s_addc_u32 s83, s83, 0
	s_waitcnt vmcnt(15)
	v_mov_b32_dpp v237, v108 row_ror:8 row_mask:0xf bank_mask:0xf
	v_mul_f32_e32 v183, v108, v168
	v_xor_b32_e32 v237, v179, v237
	v_fmac_f32_e32 v183, v237, v169
	v_mul_f32_e32 v237, v180, v183
	s_waitcnt vmcnt(14)
	v_mov_b32_dpp v238, v109 row_ror:8 row_mask:0xf bank_mask:0xf
	v_mul_f32_e32 v183, v109, v170
	v_xor_b32_e32 v238, v179, v238
	v_fmac_f32_e32 v183, v238, v171
	v_mul_f32_e32 v238, v180, v183
	s_waitcnt vmcnt(13)
	v_mov_b32_dpp v239, v110 row_ror:8 row_mask:0xf bank_mask:0xf
	v_mul_f32_e32 v183, v110, v172
	v_xor_b32_e32 v239, v179, v239
	v_fmac_f32_e32 v183, v239, v173
	v_mul_f32_e32 v239, v180, v183
	s_waitcnt vmcnt(12)
	v_mov_b32_dpp v240, v111 row_ror:8 row_mask:0xf bank_mask:0xf
	v_mul_f32_e32 v183, v111, v174
	v_xor_b32_e32 v240, v179, v240
	v_fmac_f32_e32 v183, v240, v175
	v_mul_f32_e32 v240, v180, v183
	v_cvt_pk_bf16_f32 v241, v237, v238
	v_cvt_pk_bf16_f32 v242, v239, v240
	global_store_short v229, v241, s[82:83]
	global_store_short_d16_hi v229, v241, s[82:83] offset:192
	global_store_short v229, v242, s[82:83] offset:384
	global_store_short_d16_hi v229, v242, s[82:83] offset:576
	s_add_u32 s82, s82, 1536
	s_addc_u32 s83, s83, 0
	s_branch .Lmg_qskip_22
.Lmg_qrows_23:
	v_mov_b32_e32 v231, 0x3e16c740
	v_mul_f32_e32 v184, v231, v0
	v_mul_f32_e32 v185, v231, v1
	v_mul_f32_e32 v186, v231, v2
	v_mul_f32_e32 v187, v231, v3
	v_cvt_pk_bf16_f32 v237, v184, v185
	v_cvt_pk_bf16_f32 v238, v186, v187
	global_store_short v229, v237, s[82:83]
	global_store_short_d16_hi v229, v237, s[82:83] offset:192
	global_store_short v229, v238, s[82:83] offset:384
	global_store_short_d16_hi v229, v238, s[82:83] offset:576
	s_add_u32 s82, s82, 1536
	s_addc_u32 s83, s83, 0
	v_mul_f32_e32 v184, v231, v4
	v_mul_f32_e32 v185, v231, v5
	v_mul_f32_e32 v186, v231, v6
	v_mul_f32_e32 v187, v231, v7
	v_cvt_pk_bf16_f32 v239, v184, v185
	v_cvt_pk_bf16_f32 v240, v186, v187
	global_store_short v229, v239, s[82:83]
	global_store_short_d16_hi v229, v239, s[82:83] offset:192
	global_store_short v229, v240, s[82:83] offset:384
	global_store_short_d16_hi v229, v240, s[82:83] offset:576
	s_add_u32 s82, s82, 1536
	s_addc_u32 s83, s83, 0
	v_mul_f32_e32 v184, v231, v8
	v_mul_f32_e32 v185, v231, v9
	v_mul_f32_e32 v186, v231, v10
	v_mul_f32_e32 v187, v231, v11
	v_cvt_pk_bf16_f32 v237, v184, v185
	v_cvt_pk_bf16_f32 v238, v186, v187
	global_store_short v229, v237, s[82:83]
	global_store_short_d16_hi v229, v237, s[82:83] offset:192
	global_store_short v229, v238, s[82:83] offset:384
	global_store_short_d16_hi v229, v238, s[82:83] offset:576
	s_add_u32 s82, s82, 1536
	s_addc_u32 s83, s83, 0
	v_mul_f32_e32 v184, v231, v12
	v_mul_f32_e32 v185, v231, v13
	v_mul_f32_e32 v186, v231, v14
	v_mul_f32_e32 v187, v231, v15
	v_cvt_pk_bf16_f32 v239, v184, v185
	v_cvt_pk_bf16_f32 v240, v186, v187
	global_store_short v229, v239, s[82:83]
	global_store_short_d16_hi v229, v239, s[82:83] offset:192
	global_store_short v229, v240, s[82:83] offset:384
	global_store_short_d16_hi v229, v240, s[82:83] offset:576
	s_add_u32 s82, s82, 1536
	s_addc_u32 s83, s83, 0
	v_mul_f32_e32 v184, v231, v32
	v_mul_f32_e32 v185, v231, v33
	v_mul_f32_e32 v186, v231, v34
	v_mul_f32_e32 v187, v231, v35
	v_cvt_pk_bf16_f32 v237, v184, v185
	v_cvt_pk_bf16_f32 v238, v186, v187
	global_store_short v229, v237, s[82:83]
	global_store_short_d16_hi v229, v237, s[82:83] offset:192
	global_store_short v229, v238, s[82:83] offset:384
	global_store_short_d16_hi v229, v238, s[82:83] offset:576
	s_add_u32 s82, s82, 1536
	s_addc_u32 s83, s83, 0
	v_mul_f32_e32 v184, v231, v36
	v_mul_f32_e32 v185, v231, v37
	v_mul_f32_e32 v186, v231, v38
	v_mul_f32_e32 v187, v231, v39
	v_cvt_pk_bf16_f32 v239, v184, v185
	v_cvt_pk_bf16_f32 v240, v186, v187
	global_store_short v229, v239, s[82:83]
	global_store_short_d16_hi v229, v239, s[82:83] offset:192
	global_store_short v229, v240, s[82:83] offset:384
	global_store_short_d16_hi v229, v240, s[82:83] offset:576
	s_add_u32 s82, s82, 1536
	s_addc_u32 s83, s83, 0
	v_mul_f32_e32 v184, v231, v40
	v_mul_f32_e32 v185, v231, v41
	v_mul_f32_e32 v186, v231, v42
	v_mul_f32_e32 v187, v231, v43
	v_cvt_pk_bf16_f32 v237, v184, v185
	v_cvt_pk_bf16_f32 v238, v186, v187
	global_store_short v229, v237, s[82:83]
	global_store_short_d16_hi v229, v237, s[82:83] offset:192
	global_store_short v229, v238, s[82:83] offset:384
	global_store_short_d16_hi v229, v238, s[82:83] offset:576
	s_add_u32 s82, s82, 1536
	s_addc_u32 s83, s83, 0
	v_mul_f32_e32 v184, v231, v44
	v_mul_f32_e32 v185, v231, v45
	v_mul_f32_e32 v186, v231, v46
	v_mul_f32_e32 v187, v231, v47
	v_cvt_pk_bf16_f32 v239, v184, v185
	v_cvt_pk_bf16_f32 v240, v186, v187
	global_store_short v229, v239, s[82:83]
; DI bf16_t f2bf(float x) { return (bf16_t)(pack2(x, x) & 0xffffu); }
; DI int crow(int reg, int h) { return (reg & 3) + 8 * (reg >> 2) + 4 * h; }
; template <int EPI>
; DI void epilogue(const Params& p, int layer, f32x16 (&acc)[2][2], int mrow0, int ncol0, int lane) {
;     ...
;   } else if (EPI == EPI_QUP) {
;     bf16_t* Qm = (bf16_t*)(p.ws + OFF_QM);
;     const float2* csm = (const float2*)(p.ws + OFF_ROPEM);
;     const float qs = 0.10206207261596577f * LOG2E;
;     const bool lat = mrow0 < NLAT;
;     float2 cst[2][16];
; #pragma unroll
;     for (int mi = 0; mi < 2; ++mi)
; #pragma unroll
;       for (int r = 0; r < 16; ++r) {
;         const int sq = (mrow0 + mi * 32 + crow(r, h)) & 4095;
;         const int pos = (c >> 4) ? (sq & 63) : (sq >> 6);
;         cst[mi][r] = lat ? csm[pos * 8 + (c & 7)] : make_float2(1.f, 0.f);
;       }
; #pragma unroll
;     for (int ni = 0; ni < 2; ++ni) {
;       int cg0 = ncol0 + ni * 32;
;       if (cg0 >= 576) continue;
;       int head = cg0 / 96, part = (cg0 % 96) >> 5;
; #pragma unroll
;       for (int mi = 0; mi < 2; ++mi)
; #pragma unroll
;         for (int r = 0; r < 16; ++r) {
;           int row = mrow0 + mi * 32 + crow(r, h);
;           int b, kp; row_info(row, b, kp);
;           float v = acc[mi][ni][r];
;           if (part == 2) {
;             float pv = __shfl_xor(v, 8);
;             if (lat) {
;               const float2 cs = cst[mi][r];
;               v = v * cs.x + ((c & 8) ? pv : -pv) * cs.y;
;             }
;           }
;           Qm[((size_t)(b * 6 + head) * NKEY + kp) * 96 + part * 32 + c] = f2bf(v * qs);
;         }
;     }
	global_store_short_d16_hi v229, v239, s[82:83] offset:192
	global_store_short v229, v240, s[82:83] offset:384
	global_store_short_d16_hi v229, v240, s[82:83] offset:576
	s_add_u32 s82, s82, 1536
	s_addc_u32 s83, s83, 0
	v_mul_f32_e32 v184, v231, v64
	v_mul_f32_e32 v185, v231, v65
	v_mul_f32_e32 v186, v231, v66
	v_mul_f32_e32 v187, v231, v67
	v_cvt_pk_bf16_f32 v237, v184, v185
	v_cvt_pk_bf16_f32 v238, v186, v187
	global_store_short v229, v237, s[82:83]
	global_store_short_d16_hi v229, v237, s[82:83] offset:192
	global_store_short v229, v238, s[82:83] offset:384
	global_store_short_d16_hi v229, v238, s[82:83] offset:576
	s_add_u32 s82, s82, 1536
	s_addc_u32 s83, s83, 0
	v_mul_f32_e32 v184, v231, v68
	v_mul_f32_e32 v185, v231, v69
	v_mul_f32_e32 v186, v231, v70
	v_mul_f32_e32 v187, v231, v71
	v_cvt_pk_bf16_f32 v239, v184, v185
	v_cvt_pk_bf16_f32 v240, v186, v187
	global_store_short v229, v239, s[82:83]
	global_store_short_d16_hi v229, v239, s[82:83] offset:192
	global_store_short v229, v240, s[82:83] offset:384
	global_store_short_d16_hi v229, v240, s[82:83] offset:576
	s_add_u32 s82, s82, 1536
	s_addc_u32 s83, s83, 0
	v_mul_f32_e32 v184, v231, v72
	v_mul_f32_e32 v185, v231, v73
	v_mul_f32_e32 v186, v231, v74
	v_mul_f32_e32 v187, v231, v75
	v_cvt_pk_bf16_f32 v237, v184, v185
	v_cvt_pk_bf16_f32 v238, v186, v187
	global_store_short v229, v237, s[82:83]
	global_store_short_d16_hi v229, v237, s[82:83] offset:192
	global_store_short v229, v238, s[82:83] offset:384
	global_store_short_d16_hi v229, v238, s[82:83] offset:576
	s_add_u32 s82, s82, 1536
	s_addc_u32 s83, s83, 0
	v_mul_f32_e32 v184, v231, v76
	v_mul_f32_e32 v185, v231, v77
	v_mul_f32_e32 v186, v231, v78
	v_mul_f32_e32 v187, v231, v79
	v_cvt_pk_bf16_f32 v239, v184, v185
	v_cvt_pk_bf16_f32 v240, v186, v187
	global_store_short v229, v239, s[82:83]
	global_store_short_d16_hi v229, v239, s[82:83] offset:192
	global_store_short v229, v240, s[82:83] offset:384
	global_store_short_d16_hi v229, v240, s[82:83] offset:576
	s_add_u32 s82, s82, 1536
	s_addc_u32 s83, s83, 0
	v_mul_f32_e32 v184, v231, v96
	v_mul_f32_e32 v185, v231, v97
	v_mul_f32_e32 v186, v231, v98
	v_mul_f32_e32 v187, v231, v99
	v_cvt_pk_bf16_f32 v237, v184, v185
	v_cvt_pk_bf16_f32 v238, v186, v187
	global_store_short v229, v237, s[82:83]
	global_store_short_d16_hi v229, v237, s[82:83] offset:192
	global_store_short v229, v238, s[82:83] offset:384
	global_store_short_d16_hi v229, v238, s[82:83] offset:576
	s_add_u32 s82, s82, 1536
	s_addc_u32 s83, s83, 0
	v_mul_f32_e32 v184, v231, v100
	v_mul_f32_e32 v185, v231, v101
	v_mul_f32_e32 v186, v231, v102
	v_mul_f32_e32 v187, v231, v103
	v_cvt_pk_bf16_f32 v239, v184, v185
	v_cvt_pk_bf16_f32 v240, v186, v187
	global_store_short v229, v239, s[82:83]
	global_store_short_d16_hi v229, v239, s[82:83] offset:192
	global_store_short v229, v240, s[82:83] offset:384
	global_store_short_d16_hi v229, v240, s[82:83] offset:576
	s_add_u32 s82, s82, 1536
	s_addc_u32 s83, s83, 0
	v_mul_f32_e32 v184, v231, v104
	v_mul_f32_e32 v185, v231, v105
	v_mul_f32_e32 v186, v231, v106
	v_mul_f32_e32 v187, v231, v107
	v_cvt_pk_bf16_f32 v237, v184, v185
	v_cvt_pk_bf16_f32 v238, v186, v187
	global_store_short v229, v237, s[82:83]
	global_store_short_d16_hi v229, v237, s[82:83] offset:192
	global_store_short v229, v238, s[82:83] offset:384
	global_store_short_d16_hi v229, v238, s[82:83] offset:576
	s_add_u32 s82, s82, 1536
	s_addc_u32 s83, s83, 0
	v_mul_f32_e32 v184, v231, v108
	v_mul_f32_e32 v185, v231, v109
	v_mul_f32_e32 v186, v231, v110
	v_mul_f32_e32 v187, v231, v111
	v_cvt_pk_bf16_f32 v239, v184, v185
	v_cvt_pk_bf16_f32 v240, v186, v187
	global_store_short v229, v239, s[82:83]
	global_store_short_d16_hi v229, v239, s[82:83] offset:192
	global_store_short v229, v240, s[82:83] offset:384
	global_store_short_d16_hi v229, v240, s[82:83] offset:576
	s_add_u32 s82, s82, 1536
	s_addc_u32 s83, s83, 0
.Lmg_qskip_22:
	s_lshr_b32 s28, s91, 5
	s_add_u32 s28, s28, 1
	s_cmp_ge_u32 s28, 18
	s_cbranch_scc1 .Lmg_qskip_24
	s_mul_i32 s29, s28, 43
	s_lshr_b32 s29, s29, 7
	s_mul_i32 s44, s29, 3
	s_sub_u32 s44, s28, s44
	s_mul_i32 s10, s0, 6
	s_add_u32 s10, s10, s29
	s_mul_i32 s10, s10, 4352
	s_add_u32 s10, s10, s1
	s_mul_i32 s10, s10, 192
	s_lshl_b32 s11, s44, 6
	s_add_u32 s10, s10, s11
	s_add_u32 s10, s10, 0xaa00000
	s_add_u32 s82, s24, s10
	s_addc_u32 s83, s25, 0
	s_cmp_eq_u32 s44, 2
	s_cbranch_scc0 .Lmg_qrows_25
	s_cmp_lt_u32 s67, 0x8000
	s_cbranch_scc0 .Lmg_qrows_25
; DI bf16_t f2bf(float x) { return (bf16_t)(pack2(x, x) & 0xffffu); }
; DI int crow(int reg, int h) { return (reg & 3) + 8 * (reg >> 2) + 4 * h; }
; template <int EPI>
; DI void epilogue(const Params& p, int layer, f32x16 (&acc)[2][2], int mrow0, int ncol0, int lane) {
;     ...
;   } else if (EPI == EPI_QUP) {
;     bf16_t* Qm = (bf16_t*)(p.ws + OFF_QM);
;     const float2* csm = (const float2*)(p.ws + OFF_ROPEM);
;     const float qs = 0.10206207261596577f * LOG2E;
;     const bool lat = mrow0 < NLAT;
;     float2 cst[2][16];
; #pragma unroll
;     for (int mi = 0; mi < 2; ++mi)
; #pragma unroll
;       for (int r = 0; r < 16; ++r) {
;         const int sq = (mrow0 + mi * 32 + crow(r, h)) & 4095;
;         const int pos = (c >> 4) ? (sq & 63) : (sq >> 6);
;         cst[mi][r] = lat ? csm[pos * 8 + (c & 7)] : make_float2(1.f, 0.f);
;       }
; #pragma unroll
;     for (int ni = 0; ni < 2; ++ni) {
;       int cg0 = ncol0 + ni * 32;
;       if (cg0 >= 576) continue;
;       int head = cg0 / 96, part = (cg0 % 96) >> 5;
; #pragma unroll
;       for (int mi = 0; mi < 2; ++mi)
; #pragma unroll
;         for (int r = 0; r < 16; ++r) {
;           int row = mrow0 + mi * 32 + crow(r, h);
;           int b, kp; row_info(row, b, kp);
;           float v = acc[mi][ni][r];
;           if (part == 2) {
;             float pv = __shfl_xor(v, 8);
;             if (lat) {
;               const float2 cs = cst[mi][r];
;               v = v * cs.x + ((c & 8) ? pv : -pv) * cs.y;
;             }
;           }
;           Qm[((size_t)(b * 6 + head) * NKEY + kp) * 96 + part * 32 + c] = f2bf(v * qs);
;         }
;     }
	v_lshrrev_b32_e32 v184, 4, v227
	v_lshlrev_b32_e32 v176, 6, v184
	v_sub_u32_e32 v185, 1, v184
	v_lshlrev_b32_e32 v177, 6, v185
	v_and_b32_e32 v186, 8, v227
	v_sub_u32_e32 v186, 8, v186
	v_lshlrev_b32_e32 v179, 28, v186
	v_mov_b32_e32 v180, 0x3e16c740
	v_and_b32_e32 v178, 7, v227
	v_lshlrev_b32_e32 v178, 3, v178
	v_lshlrev_b32_e32 v187, 2, v228
	v_mad_u32_u24 v178, v176, v187, v178
	s_and_b32 s12, s67, 0xfff
	s_lshr_b32 s12, s12, 6
	s_lshl_b32 s13, s78, 1
	s_add_u32 s12, s12, s13
	v_mov_b32_e32 v187, s12
	v_mad_u32_u24 v178, v177, v187, v178
	s_add_u32 s84, s24, 0x1e8d6000
	s_addc_u32 s85, s25, 0
	v_mad_u32_u24 v182, v176, 0, v178
	v_mad_u32_u24 v182, v177, 0, v182
	v_mad_u32_u24 v181, v176, 0, v182
	global_load_dwordx2 v[144:145], v181, s[84:85]
	v_mad_u32_u24 v181, v176, 1, v182
	global_load_dwordx2 v[146:147], v181, s[84:85]
	v_mad_u32_u24 v181, v176, 2, v182
	global_load_dwordx2 v[148:149], v181, s[84:85]
	v_mad_u32_u24 v181, v176, 3, v182
	global_load_dwordx2 v[150:151], v181, s[84:85]
	v_mad_u32_u24 v181, v176, 8, v182
	global_load_dwordx2 v[152:153], v181, s[84:85]
	v_mad_u32_u24 v181, v176, 9, v182
	global_load_dwordx2 v[154:155], v181, s[84:85]
	v_mad_u32_u24 v181, v176, 10, v182
	global_load_dwordx2 v[156:157], v181, s[84:85]
	v_mad_u32_u24 v181, v176, 11, v182
	global_load_dwordx2 v[158:159], v181, s[84:85]
	v_mad_u32_u24 v182, v176, 0, v178
	v_mad_u32_u24 v182, v177, 0, v182
	v_mad_u32_u24 v181, v176, 16, v182
	global_load_dwordx2 v[160:161], v181, s[84:85]
	v_mad_u32_u24 v181, v176, 17, v182
	global_load_dwordx2 v[162:163], v181, s[84:85]
	v_mad_u32_u24 v181, v176, 18, v182
	global_load_dwordx2 v[164:165], v181, s[84:85]
	v_mad_u32_u24 v181, v176, 19, v182
	global_load_dwordx2 v[166:167], v181, s[84:85]
	v_mad_u32_u24 v181, v176, 24, v182
	global_load_dwordx2 v[168:169], v181, s[84:85]
	v_mad_u32_u24 v181, v176, 25, v182
	global_load_dwordx2 v[170:171], v181, s[84:85]
	v_mad_u32_u24 v181, v176, 26, v182
	global_load_dwordx2 v[172:173], v181, s[84:85]
	v_mad_u32_u24 v181, v176, 27, v182
	global_load_dwordx2 v[174:175], v181, s[84:85]
	s_waitcnt vmcnt(15)
	v_mov_b32_dpp v237, v16 row_ror:8 row_mask:0xf bank_mask:0xf
	v_mul_f32_e32 v183, v16, v144
	v_xor_b32_e32 v237, v179, v237
	v_fmac_f32_e32 v183, v237, v145
	v_mul_f32_e32 v237, v180, v183
	s_waitcnt vmcnt(14)
	v_mov_b32_dpp v238, v17 row_ror:8 row_mask:0xf bank_mask:0xf
	v_mul_f32_e32 v183, v17, v146
	v_xor_b32_e32 v238, v179, v238
	v_fmac_f32_e32 v183, v238, v147
	v_mul_f32_e32 v238, v180, v183
	s_waitcnt vmcnt(13)
	v_mov_b32_dpp v239, v18 row_ror:8 row_mask:0xf bank_mask:0xf
	v_mul_f32_e32 v183, v18, v148
	v_xor_b32_e32 v239, v179, v239
	v_fmac_f32_e32 v183, v239, v149
	v_mul_f32_e32 v239, v180, v183
	s_waitcnt vmcnt(12)
	v_mov_b32_dpp v240, v19 row_ror:8 row_mask:0xf bank_mask:0xf
	v_mul_f32_e32 v183, v19, v150
	v_xor_b32_e32 v240, v179, v240
	v_fmac_f32_e32 v183, v240, v151
	v_mul_f32_e32 v240, v180, v183
	v_cvt_pk_bf16_f32 v241, v237, v238
	v_cvt_pk_bf16_f32 v242, v239, v240
	global_store_short v229, v241, s[82:83]
	global_store_short_d16_hi v229, v241, s[82:83] offset:192
	global_store_short v229, v242, s[82:83] offset:384
	global_store_short_d16_hi v229, v242, s[82:83] offset:576
	s_add_u32 s82, s82, 1536
	s_addc_u32 s83, s83, 0
	s_waitcnt vmcnt(15)
	v_mov_b32_dpp v237, v20 row_ror:8 row_mask:0xf bank_mask:0xf
	v_mul_f32_e32 v183, v20, v152
	v_xor_b32_e32 v237, v179, v237
	v_fmac_f32_e32 v183, v237, v153
	v_mul_f32_e32 v237, v180, v183
	s_waitcnt vmcnt(14)
	v_mov_b32_dpp v238, v21 row_ror:8 row_mask:0xf bank_mask:0xf
	v_mul_f32_e32 v183, v21, v154
	v_xor_b32_e32 v238, v179, v238
	v_fmac_f32_e32 v183, v238, v155
	v_mul_f32_e32 v238, v180, v183
	s_waitcnt vmcnt(13)
	v_mov_b32_dpp v239, v22 row_ror:8 row_mask:0xf bank_mask:0xf
	v_mul_f32_e32 v183, v22, v156
	v_xor_b32_e32 v239, v179, v239
	v_fmac_f32_e32 v183, v239, v157
	v_mul_f32_e32 v239, v180, v183
	s_waitcnt vmcnt(12)
	v_mov_b32_dpp v240, v23 row_ror:8 row_mask:0xf bank_mask:0xf
	v_mul_f32_e32 v183, v23, v158
	v_xor_b32_e32 v240, v179, v240
	v_fmac_f32_e32 v183, v240, v159
	v_mul_f32_e32 v240, v180, v183
	v_cvt_pk_bf16_f32 v241, v237, v238
	v_cvt_pk_bf16_f32 v242, v239, v240
	global_store_short v229, v241, s[82:83]
	global_store_short_d16_hi v229, v241, s[82:83] offset:192
	global_store_short v229, v242, s[82:83] offset:384
	global_store_short_d16_hi v229, v242, s[82:83] offset:576
	s_add_u32 s82, s82, 1536
	s_addc_u32 s83, s83, 0
	v_mad_u32_u24 v182, v176, 32, v178
	v_mad_u32_u24 v182, v177, 0, v182
	v_mad_u32_u24 v181, v176, 0, v182
	global_load_dwordx2 v[144:145], v181, s[84:85]
	v_mad_u32_u24 v181, v176, 1, v182
	global_load_dwordx2 v[146:147], v181, s[84:85]
	v_mad_u32_u24 v181, v176, 2, v182
	global_load_dwordx2 v[148:149], v181, s[84:85]
	v_mad_u32_u24 v181, v176, 3, v182
	global_load_dwordx2 v[150:151], v181, s[84:85]
	v_mad_u32_u24 v181, v176, 8, v182
	global_load_dwordx2 v[152:153], v181, s[84:85]
	v_mad_u32_u24 v181, v176, 9, v182
	global_load_dwordx2 v[154:155], v181, s[84:85]
	v_mad_u32_u24 v181, v176, 10, v182
	global_load_dwordx2 v[156:157], v181, s[84:85]
	v_mad_u32_u24 v181, v176, 11, v182
	global_load_dwordx2 v[158:159], v181, s[84:85]
	s_waitcnt vmcnt(23)
	v_mov_b32_dpp v237, v24 row_ror:8 row_mask:0xf bank_mask:0xf
	v_mul_f32_e32 v183, v24, v160
	v_xor_b32_e32 v237, v179, v237
	v_fmac_f32_e32 v183, v237, v161
	v_mul_f32_e32 v237, v180, v183
	s_waitcnt vmcnt(22)
	v_mov_b32_dpp v238, v25 row_ror:8 row_mask:0xf bank_mask:0xf
	v_mul_f32_e32 v183, v25, v162
	v_xor_b32_e32 v238, v179, v238
	v_fmac_f32_e32 v183, v238, v163
	v_mul_f32_e32 v238, v180, v183
	s_waitcnt vmcnt(21)
; DI bf16_t f2bf(float x) { return (bf16_t)(pack2(x, x) & 0xffffu); }
; DI int crow(int reg, int h) { return (reg & 3) + 8 * (reg >> 2) + 4 * h; }
; template <int EPI>
; DI void epilogue(const Params& p, int layer, f32x16 (&acc)[2][2], int mrow0, int ncol0, int lane) {
;     ...
;   } else if (EPI == EPI_QUP) {
;     bf16_t* Qm = (bf16_t*)(p.ws + OFF_QM);
;     const float2* csm = (const float2*)(p.ws + OFF_ROPEM);
;     const float qs = 0.10206207261596577f * LOG2E;
;     const bool lat = mrow0 < NLAT;
;     float2 cst[2][16];
; #pragma unroll
;     for (int mi = 0; mi < 2; ++mi)
; #pragma unroll
;       for (int r = 0; r < 16; ++r) {
;         const int sq = (mrow0 + mi * 32 + crow(r, h)) & 4095;
;         const int pos = (c >> 4) ? (sq & 63) : (sq >> 6);
;         cst[mi][r] = lat ? csm[pos * 8 + (c & 7)] : make_float2(1.f, 0.f);
;       }
; #pragma unroll
;     for (int ni = 0; ni < 2; ++ni) {
;       int cg0 = ncol0 + ni * 32;
;       if (cg0 >= 576) continue;
;       int head = cg0 / 96, part = (cg0 % 96) >> 5;
; #pragma unroll
;       for (int mi = 0; mi < 2; ++mi)
; #pragma unroll
;         for (int r = 0; r < 16; ++r) {
;           int row = mrow0 + mi * 32 + crow(r, h);
;           int b, kp; row_info(row, b, kp);
;           float v = acc[mi][ni][r];
;           if (part == 2) {
;             float pv = __shfl_xor(v, 8);
;             if (lat) {
;               const float2 cs = cst[mi][r];
;               v = v * cs.x + ((c & 8) ? pv : -pv) * cs.y;
;             }
;           }
;           Qm[((size_t)(b * 6 + head) * NKEY + kp) * 96 + part * 32 + c] = f2bf(v * qs);
;         }
;     }
	v_mov_b32_dpp v239, v26 row_ror:8 row_mask:0xf bank_mask:0xf
	v_mul_f32_e32 v183, v26, v164
	v_xor_b32_e32 v239, v179, v239
	v_fmac_f32_e32 v183, v239, v165
	v_mul_f32_e32 v239, v180, v183
	s_waitcnt vmcnt(20)
	v_mov_b32_dpp v240, v27 row_ror:8 row_mask:0xf bank_mask:0xf
	v_mul_f32_e32 v183, v27, v166
	v_xor_b32_e32 v240, v179, v240
	v_fmac_f32_e32 v183, v240, v167
	v_mul_f32_e32 v240, v180, v183
	v_cvt_pk_bf16_f32 v241, v237, v238
	v_cvt_pk_bf16_f32 v242, v239, v240
	global_store_short v229, v241, s[82:83]
	global_store_short_d16_hi v229, v241, s[82:83] offset:192
	global_store_short v229, v242, s[82:83] offset:384
	global_store_short_d16_hi v229, v242, s[82:83] offset:576
	s_add_u32 s82, s82, 1536
	s_addc_u32 s83, s83, 0
	s_waitcnt vmcnt(23)
	v_mov_b32_dpp v237, v28 row_ror:8 row_mask:0xf bank_mask:0xf
	v_mul_f32_e32 v183, v28, v168
	v_xor_b32_e32 v237, v179, v237
	v_fmac_f32_e32 v183, v237, v169
	v_mul_f32_e32 v237, v180, v183
	s_waitcnt vmcnt(22)
	v_mov_b32_dpp v238, v29 row_ror:8 row_mask:0xf bank_mask:0xf
	v_mul_f32_e32 v183, v29, v170
	v_xor_b32_e32 v238, v179, v238
	v_fmac_f32_e32 v183, v238, v171
	v_mul_f32_e32 v238, v180, v183
	s_waitcnt vmcnt(21)
	v_mov_b32_dpp v239, v30 row_ror:8 row_mask:0xf bank_mask:0xf
	v_mul_f32_e32 v183, v30, v172
	v_xor_b32_e32 v239, v179, v239
	v_fmac_f32_e32 v183, v239, v173
	v_mul_f32_e32 v239, v180, v183
	s_waitcnt vmcnt(20)
	v_mov_b32_dpp v240, v31 row_ror:8 row_mask:0xf bank_mask:0xf
	v_mul_f32_e32 v183, v31, v174
	v_xor_b32_e32 v240, v179, v240
	v_fmac_f32_e32 v183, v240, v175
	v_mul_f32_e32 v240, v180, v183
	v_cvt_pk_bf16_f32 v241, v237, v238
	v_cvt_pk_bf16_f32 v242, v239, v240
	global_store_short v229, v241, s[82:83]
	global_store_short_d16_hi v229, v241, s[82:83] offset:192
	global_store_short v229, v242, s[82:83] offset:384
	global_store_short_d16_hi v229, v242, s[82:83] offset:576
	s_add_u32 s82, s82, 1536
	s_addc_u32 s83, s83, 0
	v_mad_u32_u24 v182, v176, 32, v178
	v_mad_u32_u24 v182, v177, 0, v182
	v_mad_u32_u24 v181, v176, 16, v182
	global_load_dwordx2 v[160:161], v181, s[84:85]
	v_mad_u32_u24 v181, v176, 17, v182
	global_load_dwordx2 v[162:163], v181, s[84:85]
	v_mad_u32_u24 v181, v176, 18, v182
	global_load_dwordx2 v[164:165], v181, s[84:85]
	v_mad_u32_u24 v181, v176, 19, v182
	global_load_dwordx2 v[166:167], v181, s[84:85]
	v_mad_u32_u24 v181, v176, 24, v182
	global_load_dwordx2 v[168:169], v181, s[84:85]
	v_mad_u32_u24 v181, v176, 25, v182
	global_load_dwordx2 v[170:171], v181, s[84:85]
	v_mad_u32_u24 v181, v176, 26, v182
	global_load_dwordx2 v[172:173], v181, s[84:85]
	v_mad_u32_u24 v181, v176, 27, v182
	global_load_dwordx2 v[174:175], v181, s[84:85]
	s_waitcnt vmcnt(23)
	v_mov_b32_dpp v237, v48 row_ror:8 row_mask:0xf bank_mask:0xf
	v_mul_f32_e32 v183, v48, v144
	v_xor_b32_e32 v237, v179, v237
	v_fmac_f32_e32 v183, v237, v145
	v_mul_f32_e32 v237, v180, v183
	s_waitcnt vmcnt(22)
	v_mov_b32_dpp v238, v49 row_ror:8 row_mask:0xf bank_mask:0xf
	v_mul_f32_e32 v183, v49, v146
	v_xor_b32_e32 v238, v179, v238
	v_fmac_f32_e32 v183, v238, v147
	v_mul_f32_e32 v238, v180, v183
	s_waitcnt vmcnt(21)
	v_mov_b32_dpp v239, v50 row_ror:8 row_mask:0xf bank_mask:0xf
	v_mul_f32_e32 v183, v50, v148
	v_xor_b32_e32 v239, v179, v239
	v_fmac_f32_e32 v183, v239, v149
	v_mul_f32_e32 v239, v180, v183
	s_waitcnt vmcnt(20)
	v_mov_b32_dpp v240, v51 row_ror:8 row_mask:0xf bank_mask:0xf
	v_mul_f32_e32 v183, v51, v150
	v_xor_b32_e32 v240, v179, v240
	v_fmac_f32_e32 v183, v240, v151
	v_mul_f32_e32 v240, v180, v183
	v_cvt_pk_bf16_f32 v241, v237, v238
	v_cvt_pk_bf16_f32 v242, v239, v240
	global_store_short v229, v241, s[82:83]
	global_store_short_d16_hi v229, v241, s[82:83] offset:192
	global_store_short v229, v242, s[82:83] offset:384
	global_store_short_d16_hi v229, v242, s[82:83] offset:576
	s_add_u32 s82, s82, 1536
	s_addc_u32 s83, s83, 0
	s_waitcnt vmcnt(23)
	v_mov_b32_dpp v237, v52 row_ror:8 row_mask:0xf bank_mask:0xf
	v_mul_f32_e32 v183, v52, v152
	v_xor_b32_e32 v237, v179, v237
	v_fmac_f32_e32 v183, v237, v153
	v_mul_f32_e32 v237, v180, v183
	s_waitcnt vmcnt(22)
	v_mov_b32_dpp v238, v53 row_ror:8 row_mask:0xf bank_mask:0xf
	v_mul_f32_e32 v183, v53, v154
	v_xor_b32_e32 v238, v179, v238
	v_fmac_f32_e32 v183, v238, v155
	v_mul_f32_e32 v238, v180, v183
	s_waitcnt vmcnt(21)
	v_mov_b32_dpp v239, v54 row_ror:8 row_mask:0xf bank_mask:0xf
	v_mul_f32_e32 v183, v54, v156
	v_xor_b32_e32 v239, v179, v239
	v_fmac_f32_e32 v183, v239, v157
	v_mul_f32_e32 v239, v180, v183
	s_waitcnt vmcnt(20)
	v_mov_b32_dpp v240, v55 row_ror:8 row_mask:0xf bank_mask:0xf
	v_mul_f32_e32 v183, v55, v158
	v_xor_b32_e32 v240, v179, v240
	v_fmac_f32_e32 v183, v240, v159
	v_mul_f32_e32 v240, v180, v183
	v_cvt_pk_bf16_f32 v241, v237, v238
	v_cvt_pk_bf16_f32 v242, v239, v240
	global_store_short v229, v241, s[82:83]
	global_store_short_d16_hi v229, v241, s[82:83] offset:192
	global_store_short v229, v242, s[82:83] offset:384
	global_store_short_d16_hi v229, v242, s[82:83] offset:576
	s_add_u32 s82, s82, 1536
	s_addc_u32 s83, s83, 0
	v_mad_u32_u24 v182, v176, 0, v178
	v_mad_u32_u24 v182, v177, 1, v182
	v_mad_u32_u24 v181, v176, 0, v182
	global_load_dwordx2 v[144:145], v181, s[84:85]
	v_mad_u32_u24 v181, v176, 1, v182
	global_load_dwordx2 v[146:147], v181, s[84:85]
	v_mad_u32_u24 v181, v176, 2, v182
	global_load_dwordx2 v[148:149], v181, s[84:85]
	v_mad_u32_u24 v181, v176, 3, v182
	global_load_dwordx2 v[150:151], v181, s[84:85]
	v_mad_u32_u24 v181, v176, 8, v182
	global_load_dwordx2 v[152:153], v181, s[84:85]
	v_mad_u32_u24 v181, v176, 9, v182
	global_load_dwordx2 v[154:155], v181, s[84:85]
	v_mad_u32_u24 v181, v176, 10, v182
	global_load_dwordx2 v[156:157], v181, s[84:85]
	v_mad_u32_u24 v181, v176, 11, v182
	global_load_dwordx2 v[158:159], v181, s[84:85]
	s_waitcnt vmcnt(23)
; DI bf16_t f2bf(float x) { return (bf16_t)(pack2(x, x) & 0xffffu); }
; DI int crow(int reg, int h) { return (reg & 3) + 8 * (reg >> 2) + 4 * h; }
; template <int EPI>
; DI void epilogue(const Params& p, int layer, f32x16 (&acc)[2][2], int mrow0, int ncol0, int lane) {
;     ...
;   } else if (EPI == EPI_QUP) {
;     bf16_t* Qm = (bf16_t*)(p.ws + OFF_QM);
;     const float2* csm = (const float2*)(p.ws + OFF_ROPEM);
;     const float qs = 0.10206207261596577f * LOG2E;
;     const bool lat = mrow0 < NLAT;
;     float2 cst[2][16];
; #pragma unroll
;     for (int mi = 0; mi < 2; ++mi)
; #pragma unroll
;       for (int r = 0; r < 16; ++r) {
;         const int sq = (mrow0 + mi * 32 + crow(r, h)) & 4095;
;         const int pos = (c >> 4) ? (sq & 63) : (sq >> 6);
;         cst[mi][r] = lat ? csm[pos * 8 + (c & 7)] : make_float2(1.f, 0.f);
;       }
; #pragma unroll
;     for (int ni = 0; ni < 2; ++ni) {
;       int cg0 = ncol0 + ni * 32;
;       if (cg0 >= 576) continue;
;       int head = cg0 / 96, part = (cg0 % 96) >> 5;
; #pragma unroll
;       for (int mi = 0; mi < 2; ++mi)
; #pragma unroll
;         for (int r = 0; r < 16; ++r) {
;           int row = mrow0 + mi * 32 + crow(r, h);
;           int b, kp; row_info(row, b, kp);
;           float v = acc[mi][ni][r];
;           if (part == 2) {
;             float pv = __shfl_xor(v, 8);
;             if (lat) {
;               const float2 cs = cst[mi][r];
;               v = v * cs.x + ((c & 8) ? pv : -pv) * cs.y;
;             }
;           }
;           Qm[((size_t)(b * 6 + head) * NKEY + kp) * 96 + part * 32 + c] = f2bf(v * qs);
;         }
;     }
	v_mov_b32_dpp v237, v56 row_ror:8 row_mask:0xf bank_mask:0xf
	v_mul_f32_e32 v183, v56, v160
	v_xor_b32_e32 v237, v179, v237
	v_fmac_f32_e32 v183, v237, v161
	v_mul_f32_e32 v237, v180, v183
	s_waitcnt vmcnt(22)
	v_mov_b32_dpp v238, v57 row_ror:8 row_mask:0xf bank_mask:0xf
	v_mul_f32_e32 v183, v57, v162
	v_xor_b32_e32 v238, v179, v238
	v_fmac_f32_e32 v183, v238, v163
	v_mul_f32_e32 v238, v180, v183
	s_waitcnt vmcnt(21)
	v_mov_b32_dpp v239, v58 row_ror:8 row_mask:0xf bank_mask:0xf
	v_mul_f32_e32 v183, v58, v164
	v_xor_b32_e32 v239, v179, v239
	v_fmac_f32_e32 v183, v239, v165
	v_mul_f32_e32 v239, v180, v183
	s_waitcnt vmcnt(20)
	v_mov_b32_dpp v240, v59 row_ror:8 row_mask:0xf bank_mask:0xf
	v_mul_f32_e32 v183, v59, v166
	v_xor_b32_e32 v240, v179, v240
	v_fmac_f32_e32 v183, v240, v167
	v_mul_f32_e32 v240, v180, v183
	v_cvt_pk_bf16_f32 v241, v237, v238
	v_cvt_pk_bf16_f32 v242, v239, v240
	global_store_short v229, v241, s[82:83]
	global_store_short_d16_hi v229, v241, s[82:83] offset:192
	global_store_short v229, v242, s[82:83] offset:384
	global_store_short_d16_hi v229, v242, s[82:83] offset:576
	s_add_u32 s82, s82, 1536
	s_addc_u32 s83, s83, 0
	s_waitcnt vmcnt(23)
	v_mov_b32_dpp v237, v60 row_ror:8 row_mask:0xf bank_mask:0xf
	v_mul_f32_e32 v183, v60, v168
	v_xor_b32_e32 v237, v179, v237
	v_fmac_f32_e32 v183, v237, v169
	v_mul_f32_e32 v237, v180, v183
	s_waitcnt vmcnt(22)
	v_mov_b32_dpp v238, v61 row_ror:8 row_mask:0xf bank_mask:0xf
	v_mul_f32_e32 v183, v61, v170
	v_xor_b32_e32 v238, v179, v238
	v_fmac_f32_e32 v183, v238, v171
	v_mul_f32_e32 v238, v180, v183
	s_waitcnt vmcnt(21)
	v_mov_b32_dpp v239, v62 row_ror:8 row_mask:0xf bank_mask:0xf
	v_mul_f32_e32 v183, v62, v172
	v_xor_b32_e32 v239, v179, v239
	v_fmac_f32_e32 v183, v239, v173
	v_mul_f32_e32 v239, v180, v183
	s_waitcnt vmcnt(20)
	v_mov_b32_dpp v240, v63 row_ror:8 row_mask:0xf bank_mask:0xf
	v_mul_f32_e32 v183, v63, v174
	v_xor_b32_e32 v240, v179, v240
	v_fmac_f32_e32 v183, v240, v175
	v_mul_f32_e32 v240, v180, v183
	v_cvt_pk_bf16_f32 v241, v237, v238
	v_cvt_pk_bf16_f32 v242, v239, v240
	global_store_short v229, v241, s[82:83]
	global_store_short_d16_hi v229, v241, s[82:83] offset:192
	global_store_short v229, v242, s[82:83] offset:384
	global_store_short_d16_hi v229, v242, s[82:83] offset:576
	s_add_u32 s82, s82, 1536
	s_addc_u32 s83, s83, 0
	v_mad_u32_u24 v182, v176, 0, v178
	v_mad_u32_u24 v182, v177, 1, v182
	v_mad_u32_u24 v181, v176, 16, v182
	global_load_dwordx2 v[160:161], v181, s[84:85]
	v_mad_u32_u24 v181, v176, 17, v182
	global_load_dwordx2 v[162:163], v181, s[84:85]
	v_mad_u32_u24 v181, v176, 18, v182
	global_load_dwordx2 v[164:165], v181, s[84:85]
	v_mad_u32_u24 v181, v176, 19, v182
	global_load_dwordx2 v[166:167], v181, s[84:85]
	v_mad_u32_u24 v181, v176, 24, v182
	global_load_dwordx2 v[168:169], v181, s[84:85]
	v_mad_u32_u24 v181, v176, 25, v182
	global_load_dwordx2 v[170:171], v181, s[84:85]
	v_mad_u32_u24 v181, v176, 26, v182
	global_load_dwordx2 v[172:173], v181, s[84:85]
	v_mad_u32_u24 v181, v176, 27, v182
	global_load_dwordx2 v[174:175], v181, s[84:85]
	s_waitcnt vmcnt(23)
	v_mov_b32_dpp v237, v80 row_ror:8 row_mask:0xf bank_mask:0xf
	v_mul_f32_e32 v183, v80, v144
	v_xor_b32_e32 v237, v179, v237
	v_fmac_f32_e32 v183, v237, v145
	v_mul_f32_e32 v237, v180, v183
	s_waitcnt vmcnt(22)
	v_mov_b32_dpp v238, v81 row_ror:8 row_mask:0xf bank_mask:0xf
	v_mul_f32_e32 v183, v81, v146
	v_xor_b32_e32 v238, v179, v238
	v_fmac_f32_e32 v183, v238, v147
	v_mul_f32_e32 v238, v180, v183
	s_waitcnt vmcnt(21)
	v_mov_b32_dpp v239, v82 row_ror:8 row_mask:0xf bank_mask:0xf
	v_mul_f32_e32 v183, v82, v148
	v_xor_b32_e32 v239, v179, v239
	v_fmac_f32_e32 v183, v239, v149
	v_mul_f32_e32 v239, v180, v183
	s_waitcnt vmcnt(20)
	v_mov_b32_dpp v240, v83 row_ror:8 row_mask:0xf bank_mask:0xf
	v_mul_f32_e32 v183, v83, v150
	v_xor_b32_e32 v240, v179, v240
	v_fmac_f32_e32 v183, v240, v151
	v_mul_f32_e32 v240, v180, v183
	v_cvt_pk_bf16_f32 v241, v237, v238
	v_cvt_pk_bf16_f32 v242, v239, v240
	global_store_short v229, v241, s[82:83]
	global_store_short_d16_hi v229, v241, s[82:83] offset:192
	global_store_short v229, v242, s[82:83] offset:384
	global_store_short_d16_hi v229, v242, s[82:83] offset:576
	s_add_u32 s82, s82, 1536
	s_addc_u32 s83, s83, 0
	s_waitcnt vmcnt(23)
	v_mov_b32_dpp v237, v84 row_ror:8 row_mask:0xf bank_mask:0xf
	v_mul_f32_e32 v183, v84, v152
	v_xor_b32_e32 v237, v179, v237
	v_fmac_f32_e32 v183, v237, v153
	v_mul_f32_e32 v237, v180, v183
	s_waitcnt vmcnt(22)
	v_mov_b32_dpp v238, v85 row_ror:8 row_mask:0xf bank_mask:0xf
	v_mul_f32_e32 v183, v85, v154
	v_xor_b32_e32 v238, v179, v238
	v_fmac_f32_e32 v183, v238, v155
	v_mul_f32_e32 v238, v180, v183
	s_waitcnt vmcnt(21)
	v_mov_b32_dpp v239, v86 row_ror:8 row_mask:0xf bank_mask:0xf
	v_mul_f32_e32 v183, v86, v156
	v_xor_b32_e32 v239, v179, v239
	v_fmac_f32_e32 v183, v239, v157
	v_mul_f32_e32 v239, v180, v183
	s_waitcnt vmcnt(20)
	v_mov_b32_dpp v240, v87 row_ror:8 row_mask:0xf bank_mask:0xf
	v_mul_f32_e32 v183, v87, v158
	v_xor_b32_e32 v240, v179, v240
	v_fmac_f32_e32 v183, v240, v159
	v_mul_f32_e32 v240, v180, v183
	v_cvt_pk_bf16_f32 v241, v237, v238
	v_cvt_pk_bf16_f32 v242, v239, v240
	global_store_short v229, v241, s[82:83]
	global_store_short_d16_hi v229, v241, s[82:83] offset:192
	global_store_short v229, v242, s[82:83] offset:384
	global_store_short_d16_hi v229, v242, s[82:83] offset:576
	s_add_u32 s82, s82, 1536
	s_addc_u32 s83, s83, 0
	v_mad_u32_u24 v182, v176, 32, v178
	v_mad_u32_u24 v182, v177, 1, v182
	v_mad_u32_u24 v181, v176, 0, v182
	global_load_dwordx2 v[144:145], v181, s[84:85]
	v_mad_u32_u24 v181, v176, 1, v182
	global_load_dwordx2 v[146:147], v181, s[84:85]
	v_mad_u32_u24 v181, v176, 2, v182
	global_load_dwordx2 v[148:149], v181, s[84:85]
	v_mad_u32_u24 v181, v176, 3, v182
	global_load_dwordx2 v[150:151], v181, s[84:85]
	v_mad_u32_u24 v181, v176, 8, v182
	global_load_dwordx2 v[152:153], v181, s[84:85]
	v_mad_u32_u24 v181, v176, 9, v182
	global_load_dwordx2 v[154:155], v181, s[84:85]
	v_mad_u32_u24 v181, v176, 10, v182
	global_load_dwordx2 v[156:157], v181, s[84:85]
	v_mad_u32_u24 v181, v176, 11, v182
	global_load_dwordx2 v[158:159], v181, s[84:85]
	s_waitcnt vmcnt(23)
; DI bf16_t f2bf(float x) { return (bf16_t)(pack2(x, x) & 0xffffu); }
; DI int crow(int reg, int h) { return (reg & 3) + 8 * (reg >> 2) + 4 * h; }
; template <int EPI>
; DI void epilogue(const Params& p, int layer, f32x16 (&acc)[2][2], int mrow0, int ncol0, int lane) {
;     ...
;   } else if (EPI == EPI_QUP) {
;     bf16_t* Qm = (bf16_t*)(p.ws + OFF_QM);
;     const float2* csm = (const float2*)(p.ws + OFF_ROPEM);
;     const float qs = 0.10206207261596577f * LOG2E;
;     const bool lat = mrow0 < NLAT;
;     float2 cst[2][16];
; #pragma unroll
;     for (int mi = 0; mi < 2; ++mi)
; #pragma unroll
;       for (int r = 0; r < 16; ++r) {
;         const int sq = (mrow0 + mi * 32 + crow(r, h)) & 4095;
;         const int pos = (c >> 4) ? (sq & 63) : (sq >> 6);
;         cst[mi][r] = lat ? csm[pos * 8 + (c & 7)] : make_float2(1.f, 0.f);
;       }
; #pragma unroll
;     for (int ni = 0; ni < 2; ++ni) {
;       int cg0 = ncol0 + ni * 32;
;       if (cg0 >= 576) continue;
;       int head = cg0 / 96, part = (cg0 % 96) >> 5;
; #pragma unroll
;       for (int mi = 0; mi < 2; ++mi)
; #pragma unroll
;         for (int r = 0; r < 16; ++r) {
;           int row = mrow0 + mi * 32 + crow(r, h);
;           int b, kp; row_info(row, b, kp);
;           float v = acc[mi][ni][r];
;           if (part == 2) {
;             float pv = __shfl_xor(v, 8);
;             if (lat) {
;               const float2 cs = cst[mi][r];
;               v = v * cs.x + ((c & 8) ? pv : -pv) * cs.y;
;             }
;           }
;           Qm[((size_t)(b * 6 + head) * NKEY + kp) * 96 + part * 32 + c] = f2bf(v * qs);
;         }
;     }
	v_mov_b32_dpp v237, v88 row_ror:8 row_mask:0xf bank_mask:0xf
	v_mul_f32_e32 v183, v88, v160
	v_xor_b32_e32 v237, v179, v237
	v_fmac_f32_e32 v183, v237, v161
	v_mul_f32_e32 v237, v180, v183
	s_waitcnt vmcnt(22)
	v_mov_b32_dpp v238, v89 row_ror:8 row_mask:0xf bank_mask:0xf
	v_mul_f32_e32 v183, v89, v162
	v_xor_b32_e32 v238, v179, v238
	v_fmac_f32_e32 v183, v238, v163
	v_mul_f32_e32 v238, v180, v183
	s_waitcnt vmcnt(21)
	v_mov_b32_dpp v239, v90 row_ror:8 row_mask:0xf bank_mask:0xf
	v_mul_f32_e32 v183, v90, v164
	v_xor_b32_e32 v239, v179, v239
	v_fmac_f32_e32 v183, v239, v165
	v_mul_f32_e32 v239, v180, v183
	s_waitcnt vmcnt(20)
	v_mov_b32_dpp v240, v91 row_ror:8 row_mask:0xf bank_mask:0xf
	v_mul_f32_e32 v183, v91, v166
	v_xor_b32_e32 v240, v179, v240
	v_fmac_f32_e32 v183, v240, v167
	v_mul_f32_e32 v240, v180, v183
	v_cvt_pk_bf16_f32 v241, v237, v238
	v_cvt_pk_bf16_f32 v242, v239, v240
	global_store_short v229, v241, s[82:83]
	global_store_short_d16_hi v229, v241, s[82:83] offset:192
	global_store_short v229, v242, s[82:83] offset:384
	global_store_short_d16_hi v229, v242, s[82:83] offset:576
	s_add_u32 s82, s82, 1536
	s_addc_u32 s83, s83, 0
	s_waitcnt vmcnt(23)
	v_mov_b32_dpp v237, v92 row_ror:8 row_mask:0xf bank_mask:0xf
	v_mul_f32_e32 v183, v92, v168
	v_xor_b32_e32 v237, v179, v237
	v_fmac_f32_e32 v183, v237, v169
	v_mul_f32_e32 v237, v180, v183
	s_waitcnt vmcnt(22)
	v_mov_b32_dpp v238, v93 row_ror:8 row_mask:0xf bank_mask:0xf
	v_mul_f32_e32 v183, v93, v170
	v_xor_b32_e32 v238, v179, v238
	v_fmac_f32_e32 v183, v238, v171
	v_mul_f32_e32 v238, v180, v183
	s_waitcnt vmcnt(21)
	v_mov_b32_dpp v239, v94 row_ror:8 row_mask:0xf bank_mask:0xf
	v_mul_f32_e32 v183, v94, v172
	v_xor_b32_e32 v239, v179, v239
	v_fmac_f32_e32 v183, v239, v173
	v_mul_f32_e32 v239, v180, v183
	s_waitcnt vmcnt(20)
	v_mov_b32_dpp v240, v95 row_ror:8 row_mask:0xf bank_mask:0xf
	v_mul_f32_e32 v183, v95, v174
	v_xor_b32_e32 v240, v179, v240
	v_fmac_f32_e32 v183, v240, v175
	v_mul_f32_e32 v240, v180, v183
	v_cvt_pk_bf16_f32 v241, v237, v238
	v_cvt_pk_bf16_f32 v242, v239, v240
	global_store_short v229, v241, s[82:83]
	global_store_short_d16_hi v229, v241, s[82:83] offset:192
	global_store_short v229, v242, s[82:83] offset:384
	global_store_short_d16_hi v229, v242, s[82:83] offset:576
	s_add_u32 s82, s82, 1536
	s_addc_u32 s83, s83, 0
	v_mad_u32_u24 v182, v176, 32, v178
	v_mad_u32_u24 v182, v177, 1, v182
	v_mad_u32_u24 v181, v176, 16, v182
	global_load_dwordx2 v[160:161], v181, s[84:85]
	v_mad_u32_u24 v181, v176, 17, v182
	global_load_dwordx2 v[162:163], v181, s[84:85]
	v_mad_u32_u24 v181, v176, 18, v182
	global_load_dwordx2 v[164:165], v181, s[84:85]
	v_mad_u32_u24 v181, v176, 19, v182
	global_load_dwordx2 v[166:167], v181, s[84:85]
	v_mad_u32_u24 v181, v176, 24, v182
	global_load_dwordx2 v[168:169], v181, s[84:85]
	v_mad_u32_u24 v181, v176, 25, v182
	global_load_dwordx2 v[170:171], v181, s[84:85]
	v_mad_u32_u24 v181, v176, 26, v182
	global_load_dwordx2 v[172:173], v181, s[84:85]
	v_mad_u32_u24 v181, v176, 27, v182
	global_load_dwordx2 v[174:175], v181, s[84:85]
	s_waitcnt vmcnt(23)
	v_mov_b32_dpp v237, v112 row_ror:8 row_mask:0xf bank_mask:0xf
	v_mul_f32_e32 v183, v112, v144
	v_xor_b32_e32 v237, v179, v237
	v_fmac_f32_e32 v183, v237, v145
	v_mul_f32_e32 v237, v180, v183
	s_waitcnt vmcnt(22)
	v_mov_b32_dpp v238, v113 row_ror:8 row_mask:0xf bank_mask:0xf
	v_mul_f32_e32 v183, v113, v146
	v_xor_b32_e32 v238, v179, v238
	v_fmac_f32_e32 v183, v238, v147
	v_mul_f32_e32 v238, v180, v183
	s_waitcnt vmcnt(21)
	v_mov_b32_dpp v239, v114 row_ror:8 row_mask:0xf bank_mask:0xf
	v_mul_f32_e32 v183, v114, v148
	v_xor_b32_e32 v239, v179, v239
	v_fmac_f32_e32 v183, v239, v149
	v_mul_f32_e32 v239, v180, v183
	s_waitcnt vmcnt(20)
	v_mov_b32_dpp v240, v115 row_ror:8 row_mask:0xf bank_mask:0xf
	v_mul_f32_e32 v183, v115, v150
	v_xor_b32_e32 v240, v179, v240
	v_fmac_f32_e32 v183, v240, v151
	v_mul_f32_e32 v240, v180, v183
	v_cvt_pk_bf16_f32 v241, v237, v238
	v_cvt_pk_bf16_f32 v242, v239, v240
	global_store_short v229, v241, s[82:83]
	global_store_short_d16_hi v229, v241, s[82:83] offset:192
	global_store_short v229, v242, s[82:83] offset:384
	global_store_short_d16_hi v229, v242, s[82:83] offset:576
	s_add_u32 s82, s82, 1536
	s_addc_u32 s83, s83, 0
	s_waitcnt vmcnt(23)
	v_mov_b32_dpp v237, v116 row_ror:8 row_mask:0xf bank_mask:0xf
	v_mul_f32_e32 v183, v116, v152
	v_xor_b32_e32 v237, v179, v237
	v_fmac_f32_e32 v183, v237, v153
	v_mul_f32_e32 v237, v180, v183
	s_waitcnt vmcnt(22)
	v_mov_b32_dpp v238, v117 row_ror:8 row_mask:0xf bank_mask:0xf
	v_mul_f32_e32 v183, v117, v154
	v_xor_b32_e32 v238, v179, v238
	v_fmac_f32_e32 v183, v238, v155
	v_mul_f32_e32 v238, v180, v183
	s_waitcnt vmcnt(21)
	v_mov_b32_dpp v239, v118 row_ror:8 row_mask:0xf bank_mask:0xf
	v_mul_f32_e32 v183, v118, v156
	v_xor_b32_e32 v239, v179, v239
	v_fmac_f32_e32 v183, v239, v157
	v_mul_f32_e32 v239, v180, v183
	s_waitcnt vmcnt(20)
	v_mov_b32_dpp v240, v119 row_ror:8 row_mask:0xf bank_mask:0xf
	v_mul_f32_e32 v183, v119, v158
	v_xor_b32_e32 v240, v179, v240
	v_fmac_f32_e32 v183, v240, v159
	v_mul_f32_e32 v240, v180, v183
	v_cvt_pk_bf16_f32 v241, v237, v238
	v_cvt_pk_bf16_f32 v242, v239, v240
	global_store_short v229, v241, s[82:83]
	global_store_short_d16_hi v229, v241, s[82:83] offset:192
	global_store_short v229, v242, s[82:83] offset:384
	global_store_short_d16_hi v229, v242, s[82:83] offset:576
	s_add_u32 s82, s82, 1536
	s_addc_u32 s83, s83, 0
	s_waitcnt vmcnt(15)
	v_mov_b32_dpp v237, v120 row_ror:8 row_mask:0xf bank_mask:0xf
	v_mul_f32_e32 v183, v120, v160
	v_xor_b32_e32 v237, v179, v237
	v_fmac_f32_e32 v183, v237, v161
	v_mul_f32_e32 v237, v180, v183
	s_waitcnt vmcnt(14)
; DI bf16_t f2bf(float x) { return (bf16_t)(pack2(x, x) & 0xffffu); }
; DI int crow(int reg, int h) { return (reg & 3) + 8 * (reg >> 2) + 4 * h; }
; template <int EPI>
; DI void epilogue(const Params& p, int layer, f32x16 (&acc)[2][2], int mrow0, int ncol0, int lane) {
;     ...
;   } else if (EPI == EPI_QUP) {
;     bf16_t* Qm = (bf16_t*)(p.ws + OFF_QM);
;     const float2* csm = (const float2*)(p.ws + OFF_ROPEM);
;     const float qs = 0.10206207261596577f * LOG2E;
;     const bool lat = mrow0 < NLAT;
;     float2 cst[2][16];
; #pragma unroll
;     for (int mi = 0; mi < 2; ++mi)
; #pragma unroll
;       for (int r = 0; r < 16; ++r) {
;         const int sq = (mrow0 + mi * 32 + crow(r, h)) & 4095;
;         const int pos = (c >> 4) ? (sq & 63) : (sq >> 6);
;         cst[mi][r] = lat ? csm[pos * 8 + (c & 7)] : make_float2(1.f, 0.f);
;       }
; #pragma unroll
;     for (int ni = 0; ni < 2; ++ni) {
;       int cg0 = ncol0 + ni * 32;
;       if (cg0 >= 576) continue;
;       int head = cg0 / 96, part = (cg0 % 96) >> 5;
; #pragma unroll
;       for (int mi = 0; mi < 2; ++mi)
; #pragma unroll
;         for (int r = 0; r < 16; ++r) {
;           int row = mrow0 + mi * 32 + crow(r, h);
;           int b, kp; row_info(row, b, kp);
;           float v = acc[mi][ni][r];
;           if (part == 2) {
;             float pv = __shfl_xor(v, 8);
;             if (lat) {
;               const float2 cs = cst[mi][r];
;               v = v * cs.x + ((c & 8) ? pv : -pv) * cs.y;
;             }
;           }
;           Qm[((size_t)(b * 6 + head) * NKEY + kp) * 96 + part * 32 + c] = f2bf(v * qs);
;         }
;     }
	v_mov_b32_dpp v238, v121 row_ror:8 row_mask:0xf bank_mask:0xf
	v_mul_f32_e32 v183, v121, v162
	v_xor_b32_e32 v238, v179, v238
	v_fmac_f32_e32 v183, v238, v163
	v_mul_f32_e32 v238, v180, v183
	s_waitcnt vmcnt(13)
	v_mov_b32_dpp v239, v122 row_ror:8 row_mask:0xf bank_mask:0xf
	v_mul_f32_e32 v183, v122, v164
	v_xor_b32_e32 v239, v179, v239
	v_fmac_f32_e32 v183, v239, v165
	v_mul_f32_e32 v239, v180, v183
	s_waitcnt vmcnt(12)
	v_mov_b32_dpp v240, v123 row_ror:8 row_mask:0xf bank_mask:0xf
	v_mul_f32_e32 v183, v123, v166
	v_xor_b32_e32 v240, v179, v240
	v_fmac_f32_e32 v183, v240, v167
	v_mul_f32_e32 v240, v180, v183
	v_cvt_pk_bf16_f32 v241, v237, v238
	v_cvt_pk_bf16_f32 v242, v239, v240
	global_store_short v229, v241, s[82:83]
	global_store_short_d16_hi v229, v241, s[82:83] offset:192
	global_store_short v229, v242, s[82:83] offset:384
	global_store_short_d16_hi v229, v242, s[82:83] offset:576
	s_add_u32 s82, s82, 1536
	s_addc_u32 s83, s83, 0
	s_waitcnt vmcnt(15)
	v_mov_b32_dpp v237, v124 row_ror:8 row_mask:0xf bank_mask:0xf
	v_mul_f32_e32 v183, v124, v168
	v_xor_b32_e32 v237, v179, v237
	v_fmac_f32_e32 v183, v237, v169
	v_mul_f32_e32 v237, v180, v183
	s_waitcnt vmcnt(14)
	v_mov_b32_dpp v238, v125 row_ror:8 row_mask:0xf bank_mask:0xf
	v_mul_f32_e32 v183, v125, v170
	v_xor_b32_e32 v238, v179, v238
	v_fmac_f32_e32 v183, v238, v171
	v_mul_f32_e32 v238, v180, v183
	s_waitcnt vmcnt(13)
	v_mov_b32_dpp v239, v126 row_ror:8 row_mask:0xf bank_mask:0xf
	v_mul_f32_e32 v183, v126, v172
	v_xor_b32_e32 v239, v179, v239
	v_fmac_f32_e32 v183, v239, v173
	v_mul_f32_e32 v239, v180, v183
	s_waitcnt vmcnt(12)
	v_mov_b32_dpp v240, v127 row_ror:8 row_mask:0xf bank_mask:0xf
	v_mul_f32_e32 v183, v127, v174
	v_xor_b32_e32 v240, v179, v240
	v_fmac_f32_e32 v183, v240, v175
	v_mul_f32_e32 v240, v180, v183
	v_cvt_pk_bf16_f32 v241, v237, v238
	v_cvt_pk_bf16_f32 v242, v239, v240
	global_store_short v229, v241, s[82:83]
	global_store_short_d16_hi v229, v241, s[82:83] offset:192
	global_store_short v229, v242, s[82:83] offset:384
	global_store_short_d16_hi v229, v242, s[82:83] offset:576
	s_add_u32 s82, s82, 1536
	s_addc_u32 s83, s83, 0
	s_branch .Lmg_qskip_24
.Lmg_qrows_25:
	v_mov_b32_e32 v231, 0x3e16c740
	v_mul_f32_e32 v184, v231, v16
	v_mul_f32_e32 v185, v231, v17
	v_mul_f32_e32 v186, v231, v18
	v_mul_f32_e32 v187, v231, v19
	v_cvt_pk_bf16_f32 v237, v184, v185
	v_cvt_pk_bf16_f32 v238, v186, v187
	global_store_short v229, v237, s[82:83]
	global_store_short_d16_hi v229, v237, s[82:83] offset:192
	global_store_short v229, v238, s[82:83] offset:384
	global_store_short_d16_hi v229, v238, s[82:83] offset:576
	s_add_u32 s82, s82, 1536
	s_addc_u32 s83, s83, 0
	v_mul_f32_e32 v184, v231, v20
	v_mul_f32_e32 v185, v231, v21
	v_mul_f32_e32 v186, v231, v22
	v_mul_f32_e32 v187, v231, v23
	v_cvt_pk_bf16_f32 v239, v184, v185
	v_cvt_pk_bf16_f32 v240, v186, v187
	global_store_short v229, v239, s[82:83]
	global_store_short_d16_hi v229, v239, s[82:83] offset:192
	global_store_short v229, v240, s[82:83] offset:384
	global_store_short_d16_hi v229, v240, s[82:83] offset:576
	s_add_u32 s82, s82, 1536
	s_addc_u32 s83, s83, 0
	v_mul_f32_e32 v184, v231, v24
	v_mul_f32_e32 v185, v231, v25
	v_mul_f32_e32 v186, v231, v26
	v_mul_f32_e32 v187, v231, v27
	v_cvt_pk_bf16_f32 v237, v184, v185
	v_cvt_pk_bf16_f32 v238, v186, v187
	global_store_short v229, v237, s[82:83]
	global_store_short_d16_hi v229, v237, s[82:83] offset:192
	global_store_short v229, v238, s[82:83] offset:384
	global_store_short_d16_hi v229, v238, s[82:83] offset:576
	s_add_u32 s82, s82, 1536
	s_addc_u32 s83, s83, 0
	v_mul_f32_e32 v184, v231, v28
	v_mul_f32_e32 v185, v231, v29
	v_mul_f32_e32 v186, v231, v30
	v_mul_f32_e32 v187, v231, v31
	v_cvt_pk_bf16_f32 v239, v184, v185
	v_cvt_pk_bf16_f32 v240, v186, v187
	global_store_short v229, v239, s[82:83]
	global_store_short_d16_hi v229, v239, s[82:83] offset:192
	global_store_short v229, v240, s[82:83] offset:384
	global_store_short_d16_hi v229, v240, s[82:83] offset:576
	s_add_u32 s82, s82, 1536
	s_addc_u32 s83, s83, 0
	v_mul_f32_e32 v184, v231, v48
	v_mul_f32_e32 v185, v231, v49
	v_mul_f32_e32 v186, v231, v50
	v_mul_f32_e32 v187, v231, v51
	v_cvt_pk_bf16_f32 v237, v184, v185
	v_cvt_pk_bf16_f32 v238, v186, v187
	global_store_short v229, v237, s[82:83]
	global_store_short_d16_hi v229, v237, s[82:83] offset:192
	global_store_short v229, v238, s[82:83] offset:384
	global_store_short_d16_hi v229, v238, s[82:83] offset:576
	s_add_u32 s82, s82, 1536
	s_addc_u32 s83, s83, 0
	v_mul_f32_e32 v184, v231, v52
	v_mul_f32_e32 v185, v231, v53
	v_mul_f32_e32 v186, v231, v54
	v_mul_f32_e32 v187, v231, v55
	v_cvt_pk_bf16_f32 v239, v184, v185
	v_cvt_pk_bf16_f32 v240, v186, v187
	global_store_short v229, v239, s[82:83]
	global_store_short_d16_hi v229, v239, s[82:83] offset:192
; DI bf16_t f2bf(float x) { return (bf16_t)(pack2(x, x) & 0xffffu); }
; DI int crow(int reg, int h) { return (reg & 3) + 8 * (reg >> 2) + 4 * h; }
; template <int EPI>
; DI void epilogue(const Params& p, int layer, f32x16 (&acc)[2][2], int mrow0, int ncol0, int lane) {
;     ...
;     for (int ni = 0; ni < 2; ++ni) {
;       int cg0 = ncol0 + ni * 32;
;       if (cg0 >= 576) continue;
;       int head = cg0 / 96, part = (cg0 % 96) >> 5;
; #pragma unroll
;       for (int mi = 0; mi < 2; ++mi)
; #pragma unroll
;         for (int r = 0; r < 16; ++r) {
;           int row = mrow0 + mi * 32 + crow(r, h);
;           int b, kp; row_info(row, b, kp);
;           float v = acc[mi][ni][r];
;           if (part == 2) {
;             float pv = __shfl_xor(v, 8);
;             if (lat) {
;               const float2 cs = cst[mi][r];
;               v = v * cs.x + ((c & 8) ? pv : -pv) * cs.y;
;             }
;           }
;           Qm[((size_t)(b * 6 + head) * NKEY + kp) * 96 + part * 32 + c] = f2bf(v * qs);
;         }
	global_store_short v229, v240, s[82:83] offset:384
	global_store_short_d16_hi v229, v240, s[82:83] offset:576
	s_add_u32 s82, s82, 1536
	s_addc_u32 s83, s83, 0
	v_mul_f32_e32 v184, v231, v56
	v_mul_f32_e32 v185, v231, v57
	v_mul_f32_e32 v186, v231, v58
	v_mul_f32_e32 v187, v231, v59
	v_cvt_pk_bf16_f32 v237, v184, v185
	v_cvt_pk_bf16_f32 v238, v186, v187
	global_store_short v229, v237, s[82:83]
	global_store_short_d16_hi v229, v237, s[82:83] offset:192
	global_store_short v229, v238, s[82:83] offset:384
	global_store_short_d16_hi v229, v238, s[82:83] offset:576
	s_add_u32 s82, s82, 1536
	s_addc_u32 s83, s83, 0
	v_mul_f32_e32 v184, v231, v60
	v_mul_f32_e32 v185, v231, v61
	v_mul_f32_e32 v186, v231, v62
	v_mul_f32_e32 v187, v231, v63
	v_cvt_pk_bf16_f32 v239, v184, v185
	v_cvt_pk_bf16_f32 v240, v186, v187
	global_store_short v229, v239, s[82:83]
	global_store_short_d16_hi v229, v239, s[82:83] offset:192
	global_store_short v229, v240, s[82:83] offset:384
	global_store_short_d16_hi v229, v240, s[82:83] offset:576
	s_add_u32 s82, s82, 1536
	s_addc_u32 s83, s83, 0
	v_mul_f32_e32 v184, v231, v80
	v_mul_f32_e32 v185, v231, v81
	v_mul_f32_e32 v186, v231, v82
	v_mul_f32_e32 v187, v231, v83
	v_cvt_pk_bf16_f32 v237, v184, v185
	v_cvt_pk_bf16_f32 v238, v186, v187
	global_store_short v229, v237, s[82:83]
	global_store_short_d16_hi v229, v237, s[82:83] offset:192
	global_store_short v229, v238, s[82:83] offset:384
	global_store_short_d16_hi v229, v238, s[82:83] offset:576
	s_add_u32 s82, s82, 1536
	s_addc_u32 s83, s83, 0
	v_mul_f32_e32 v184, v231, v84
	v_mul_f32_e32 v185, v231, v85
	v_mul_f32_e32 v186, v231, v86
	v_mul_f32_e32 v187, v231, v87
	v_cvt_pk_bf16_f32 v239, v184, v185
	v_cvt_pk_bf16_f32 v240, v186, v187
	global_store_short v229, v239, s[82:83]
	global_store_short_d16_hi v229, v239, s[82:83] offset:192
	global_store_short v229, v240, s[82:83] offset:384
	global_store_short_d16_hi v229, v240, s[82:83] offset:576
	s_add_u32 s82, s82, 1536
	s_addc_u32 s83, s83, 0
	v_mul_f32_e32 v184, v231, v88
	v_mul_f32_e32 v185, v231, v89
	v_mul_f32_e32 v186, v231, v90
	v_mul_f32_e32 v187, v231, v91
	v_cvt_pk_bf16_f32 v237, v184, v185
	v_cvt_pk_bf16_f32 v238, v186, v187
	global_store_short v229, v237, s[82:83]
	global_store_short_d16_hi v229, v237, s[82:83] offset:192
	global_store_short v229, v238, s[82:83] offset:384
	global_store_short_d16_hi v229, v238, s[82:83] offset:576
	s_add_u32 s82, s82, 1536
	s_addc_u32 s83, s83, 0
	v_mul_f32_e32 v184, v231, v92
	v_mul_f32_e32 v185, v231, v93
	v_mul_f32_e32 v186, v231, v94
	v_mul_f32_e32 v187, v231, v95
	v_cvt_pk_bf16_f32 v239, v184, v185
	v_cvt_pk_bf16_f32 v240, v186, v187
	global_store_short v229, v239, s[82:83]
	global_store_short_d16_hi v229, v239, s[82:83] offset:192
	global_store_short v229, v240, s[82:83] offset:384
	global_store_short_d16_hi v229, v240, s[82:83] offset:576
	s_add_u32 s82, s82, 1536
	s_addc_u32 s83, s83, 0
	v_mul_f32_e32 v184, v231, v112
	v_mul_f32_e32 v185, v231, v113
	v_mul_f32_e32 v186, v231, v114
	v_mul_f32_e32 v187, v231, v115
	v_cvt_pk_bf16_f32 v237, v184, v185
	v_cvt_pk_bf16_f32 v238, v186, v187
	global_store_short v229, v237, s[82:83]
	global_store_short_d16_hi v229, v237, s[82:83] offset:192
	global_store_short v229, v238, s[82:83] offset:384
	global_store_short_d16_hi v229, v238, s[82:83] offset:576
	s_add_u32 s82, s82, 1536
	s_addc_u32 s83, s83, 0
	v_mul_f32_e32 v184, v231, v116
	v_mul_f32_e32 v185, v231, v117
	v_mul_f32_e32 v186, v231, v118
	v_mul_f32_e32 v187, v231, v119
	v_cvt_pk_bf16_f32 v239, v184, v185
	v_cvt_pk_bf16_f32 v240, v186, v187
	global_store_short v229, v239, s[82:83]
	global_store_short_d16_hi v229, v239, s[82:83] offset:192
	global_store_short v229, v240, s[82:83] offset:384
	global_store_short_d16_hi v229, v240, s[82:83] offset:576
	s_add_u32 s82, s82, 1536
	s_addc_u32 s83, s83, 0
	v_mul_f32_e32 v184, v231, v120
	v_mul_f32_e32 v185, v231, v121
	v_mul_f32_e32 v186, v231, v122
	v_mul_f32_e32 v187, v231, v123
	v_cvt_pk_bf16_f32 v237, v184, v185
	v_cvt_pk_bf16_f32 v238, v186, v187
	global_store_short v229, v237, s[82:83]
	global_store_short_d16_hi v229, v237, s[82:83] offset:192
	global_store_short v229, v238, s[82:83] offset:384
	global_store_short_d16_hi v229, v238, s[82:83] offset:576
	s_add_u32 s82, s82, 1536
	s_addc_u32 s83, s83, 0
	v_mul_f32_e32 v184, v231, v124
	v_mul_f32_e32 v185, v231, v125
	v_mul_f32_e32 v186, v231, v126
	v_mul_f32_e32 v187, v231, v127
	v_cvt_pk_bf16_f32 v239, v184, v185
	v_cvt_pk_bf16_f32 v240, v186, v187
	global_store_short v229, v239, s[82:83]
	global_store_short_d16_hi v229, v239, s[82:83] offset:192
	global_store_short v229, v240, s[82:83] offset:384
	global_store_short_d16_hi v229, v240, s[82:83] offset:576
	s_add_u32 s82, s82, 1536
	s_addc_u32 s83, s83, 0

; DI bf16_t f2bf(float x) { return (bf16_t)(pack2(x, x) & 0xffffu); }
; DI int crow(int reg, int h) { return (reg & 3) + 8 * (reg >> 2) + 4 * h; }
; template <int EPI>
; DI void epilogue(const Params& p, int layer, f32x16 (&acc)[2][2], int mrow0, int ncol0, int lane) {
;     ...
;   } else if (EPI == EPI_KVUP) {
;     bf16_t* Km = (bf16_t*)(p.ws + OFF_KM);
;     bf16_t* Vmt = (bf16_t*)(p.ws + OFF_VMT);
; #pragma unroll
;     for (int ni = 0; ni < 2; ++ni) {
;       int cg0 = ncol0 + ni * 32;
;       int head = cg0 >> 7, part = (cg0 >> 5) & 3;
; #pragma unroll
;       for (int mi = 0; mi < 2; ++mi) {
;         if (part < 2) {
; #pragma unroll
;           for (int r = 0; r < 16; ++r) {
;             int row = mrow0 + mi * 32 + crow(r, h);
;             int b, kp; row_info(row, b, kp);
;             Km[((size_t)(b * 6 + head) * NKEY + kp) * 96 + part * 32 + c] = f2bf(acc[mi][ni][r]);
;           }
.Lmg_bj_27:
	s_lshl_b32 s10, s78, 7
	s_add_u32 s1, s1, s10
	s_lshr_b32 s29, s68, 7
	s_cmp_eq_u32 s79, 0
	s_cbranch_scc0 .Lmg_kvv_28
	v_lshlrev_b32_e32 v229, 1, v227
	s_movk_i32 s10, 768
	v_mad_u32_u24 v229, v228, s10, v229
	s_mov_b32 s44, 0
	s_mul_i32 s10, s0, 6
	s_add_u32 s10, s10, s29
	s_mul_i32 s10, s10, 4352
	s_add_u32 s10, s10, s1
	s_mul_i32 s10, s10, 192
	s_lshl_b32 s11, s44, 6
	s_add_u32 s10, s10, s11
	s_add_u32 s10, s10, 0xd040000
	s_add_u32 s82, s24, s10
	s_addc_u32 s83, s25, 0
	v_cvt_pk_bf16_f32 v237, v0, v1
	v_cvt_pk_bf16_f32 v238, v2, v3
	global_store_short v229, v237, s[82:83]
	global_store_short_d16_hi v229, v237, s[82:83] offset:192
	global_store_short v229, v238, s[82:83] offset:384
	global_store_short_d16_hi v229, v238, s[82:83] offset:576
	s_add_u32 s82, s82, 1536
	s_addc_u32 s83, s83, 0
	v_cvt_pk_bf16_f32 v239, v4, v5
	v_cvt_pk_bf16_f32 v240, v6, v7
	global_store_short v229, v239, s[82:83]
	global_store_short_d16_hi v229, v239, s[82:83] offset:192
	global_store_short v229, v240, s[82:83] offset:384
	global_store_short_d16_hi v229, v240, s[82:83] offset:576
	s_add_u32 s82, s82, 1536
	s_addc_u32 s83, s83, 0
	v_cvt_pk_bf16_f32 v237, v8, v9
	v_cvt_pk_bf16_f32 v238, v10, v11
	global_store_short v229, v237, s[82:83]
	global_store_short_d16_hi v229, v237, s[82:83] offset:192
	global_store_short v229, v238, s[82:83] offset:384
	global_store_short_d16_hi v229, v238, s[82:83] offset:576
	s_add_u32 s82, s82, 1536
	s_addc_u32 s83, s83, 0
	v_cvt_pk_bf16_f32 v239, v12, v13
	v_cvt_pk_bf16_f32 v240, v14, v15
	global_store_short v229, v239, s[82:83]
	global_store_short_d16_hi v229, v239, s[82:83] offset:192
	global_store_short v229, v240, s[82:83] offset:384
	global_store_short_d16_hi v229, v240, s[82:83] offset:576
	s_add_u32 s82, s82, 1536
	s_addc_u32 s83, s83, 0
	v_cvt_pk_bf16_f32 v237, v32, v33
	v_cvt_pk_bf16_f32 v238, v34, v35
	global_store_short v229, v237, s[82:83]
	global_store_short_d16_hi v229, v237, s[82:83] offset:192
	global_store_short v229, v238, s[82:83] offset:384
	global_store_short_d16_hi v229, v238, s[82:83] offset:576
	s_add_u32 s82, s82, 1536
	s_addc_u32 s83, s83, 0
	v_cvt_pk_bf16_f32 v239, v36, v37
	v_cvt_pk_bf16_f32 v240, v38, v39
	global_store_short v229, v239, s[82:83]
	global_store_short_d16_hi v229, v239, s[82:83] offset:192
	global_store_short v229, v240, s[82:83] offset:384
	global_store_short_d16_hi v229, v240, s[82:83] offset:576
	s_add_u32 s82, s82, 1536
	s_addc_u32 s83, s83, 0
	v_cvt_pk_bf16_f32 v237, v40, v41
	v_cvt_pk_bf16_f32 v238, v42, v43
	global_store_short v229, v237, s[82:83]
	global_store_short_d16_hi v229, v237, s[82:83] offset:192
	global_store_short v229, v238, s[82:83] offset:384
	global_store_short_d16_hi v229, v238, s[82:83] offset:576
	s_add_u32 s82, s82, 1536
	s_addc_u32 s83, s83, 0
	v_cvt_pk_bf16_f32 v239, v44, v45
	v_cvt_pk_bf16_f32 v240, v46, v47
	global_store_short v229, v239, s[82:83]
	global_store_short_d16_hi v229, v239, s[82:83] offset:192
	global_store_short v229, v240, s[82:83] offset:384
	global_store_short_d16_hi v229, v240, s[82:83] offset:576
	s_add_u32 s82, s82, 1536
	s_addc_u32 s83, s83, 0
	v_cvt_pk_bf16_f32 v237, v64, v65
	v_cvt_pk_bf16_f32 v238, v66, v67
	global_store_short v229, v237, s[82:83]
	global_store_short_d16_hi v229, v237, s[82:83] offset:192
	global_store_short v229, v238, s[82:83] offset:384
	global_store_short_d16_hi v229, v238, s[82:83] offset:576
	s_add_u32 s82, s82, 1536
	s_addc_u32 s83, s83, 0
	v_cvt_pk_bf16_f32 v239, v68, v69
	v_cvt_pk_bf16_f32 v240, v70, v71
	global_store_short v229, v239, s[82:83]
	global_store_short_d16_hi v229, v239, s[82:83] offset:192
	global_store_short v229, v240, s[82:83] offset:384
	global_store_short_d16_hi v229, v240, s[82:83] offset:576
	s_add_u32 s82, s82, 1536
	s_addc_u32 s83, s83, 0
	v_cvt_pk_bf16_f32 v237, v72, v73
	v_cvt_pk_bf16_f32 v238, v74, v75
	global_store_short v229, v237, s[82:83]
	global_store_short_d16_hi v229, v237, s[82:83] offset:192
	global_store_short v229, v238, s[82:83] offset:384
	global_store_short_d16_hi v229, v238, s[82:83] offset:576
	s_add_u32 s82, s82, 1536
	s_addc_u32 s83, s83, 0
	v_cvt_pk_bf16_f32 v239, v76, v77
	v_cvt_pk_bf16_f32 v240, v78, v79
	global_store_short v229, v239, s[82:83]
	global_store_short_d16_hi v229, v239, s[82:83] offset:192
	global_store_short v229, v240, s[82:83] offset:384
	global_store_short_d16_hi v229, v240, s[82:83] offset:576
	s_add_u32 s82, s82, 1536
	s_addc_u32 s83, s83, 0
	v_cvt_pk_bf16_f32 v237, v96, v97
	v_cvt_pk_bf16_f32 v238, v98, v99
	global_store_short v229, v237, s[82:83]
	global_store_short_d16_hi v229, v237, s[82:83] offset:192
	global_store_short v229, v238, s[82:83] offset:384
	global_store_short_d16_hi v229, v238, s[82:83] offset:576
	s_add_u32 s82, s82, 1536
	s_addc_u32 s83, s83, 0
	v_cvt_pk_bf16_f32 v239, v100, v101
	v_cvt_pk_bf16_f32 v240, v102, v103
	global_store_short v229, v239, s[82:83]
	global_store_short_d16_hi v229, v239, s[82:83] offset:192
	global_store_short v229, v240, s[82:83] offset:384
	global_store_short_d16_hi v229, v240, s[82:83] offset:576
	s_add_u32 s82, s82, 1536
	s_addc_u32 s83, s83, 0
	v_cvt_pk_bf16_f32 v237, v104, v105
	v_cvt_pk_bf16_f32 v238, v106, v107
	global_store_short v229, v237, s[82:83]
	global_store_short_d16_hi v229, v237, s[82:83] offset:192
	global_store_short v229, v238, s[82:83] offset:384
	global_store_short_d16_hi v229, v238, s[82:83] offset:576
	s_add_u32 s82, s82, 1536
	s_addc_u32 s83, s83, 0
	v_cvt_pk_bf16_f32 v239, v108, v109
	v_cvt_pk_bf16_f32 v240, v110, v111
	global_store_short v229, v239, s[82:83]
	global_store_short_d16_hi v229, v239, s[82:83] offset:192
	global_store_short v229, v240, s[82:83] offset:384
; DI bf16_t f2bf(float x) { return (bf16_t)(pack2(x, x) & 0xffffu); }
; DI int crow(int reg, int h) { return (reg & 3) + 8 * (reg >> 2) + 4 * h; }
; template <int EPI>
; DI void epilogue(const Params& p, int layer, f32x16 (&acc)[2][2], int mrow0, int ncol0, int lane) {
;     ...
;     for (int ni = 0; ni < 2; ++ni) {
;       int cg0 = ncol0 + ni * 32;
;       int head = cg0 >> 7, part = (cg0 >> 5) & 3;
; #pragma unroll
;       for (int mi = 0; mi < 2; ++mi) {
;         if (part < 2) {
; #pragma unroll
;           for (int r = 0; r < 16; ++r) {
;             int row = mrow0 + mi * 32 + crow(r, h);
;             int b, kp; row_info(row, b, kp);
;             Km[((size_t)(b * 6 + head) * NKEY + kp) * 96 + part * 32 + c] = f2bf(acc[mi][ni][r]);
;           }
	global_store_short_d16_hi v229, v240, s[82:83] offset:576
	s_add_u32 s82, s82, 1536
	s_addc_u32 s83, s83, 0
	s_mov_b32 s44, 1
	s_mul_i32 s10, s0, 6
	s_add_u32 s10, s10, s29
	s_mul_i32 s10, s10, 4352
	s_add_u32 s10, s10, s1
	s_mul_i32 s10, s10, 192
	s_lshl_b32 s11, s44, 6
	s_add_u32 s10, s10, s11
	s_add_u32 s10, s10, 0xd040000
	s_add_u32 s82, s24, s10
	s_addc_u32 s83, s25, 0
	v_cvt_pk_bf16_f32 v237, v16, v17
	v_cvt_pk_bf16_f32 v238, v18, v19
	global_store_short v229, v237, s[82:83]
	global_store_short_d16_hi v229, v237, s[82:83] offset:192
	global_store_short v229, v238, s[82:83] offset:384
	global_store_short_d16_hi v229, v238, s[82:83] offset:576
	s_add_u32 s82, s82, 1536
	s_addc_u32 s83, s83, 0
	v_cvt_pk_bf16_f32 v239, v20, v21
	v_cvt_pk_bf16_f32 v240, v22, v23
	global_store_short v229, v239, s[82:83]
	global_store_short_d16_hi v229, v239, s[82:83] offset:192
	global_store_short v229, v240, s[82:83] offset:384
	global_store_short_d16_hi v229, v240, s[82:83] offset:576
	s_add_u32 s82, s82, 1536
	s_addc_u32 s83, s83, 0
	v_cvt_pk_bf16_f32 v237, v24, v25
	v_cvt_pk_bf16_f32 v238, v26, v27
	global_store_short v229, v237, s[82:83]
	global_store_short_d16_hi v229, v237, s[82:83] offset:192
	global_store_short v229, v238, s[82:83] offset:384
	global_store_short_d16_hi v229, v238, s[82:83] offset:576
	s_add_u32 s82, s82, 1536
	s_addc_u32 s83, s83, 0
	v_cvt_pk_bf16_f32 v239, v28, v29
	v_cvt_pk_bf16_f32 v240, v30, v31
	global_store_short v229, v239, s[82:83]
	global_store_short_d16_hi v229, v239, s[82:83] offset:192
	global_store_short v229, v240, s[82:83] offset:384
	global_store_short_d16_hi v229, v240, s[82:83] offset:576
	s_add_u32 s82, s82, 1536
	s_addc_u32 s83, s83, 0
	v_cvt_pk_bf16_f32 v237, v48, v49
	v_cvt_pk_bf16_f32 v238, v50, v51
	global_store_short v229, v237, s[82:83]
	global_store_short_d16_hi v229, v237, s[82:83] offset:192
	global_store_short v229, v238, s[82:83] offset:384
	global_store_short_d16_hi v229, v238, s[82:83] offset:576
	s_add_u32 s82, s82, 1536
	s_addc_u32 s83, s83, 0
	v_cvt_pk_bf16_f32 v239, v52, v53
	v_cvt_pk_bf16_f32 v240, v54, v55
	global_store_short v229, v239, s[82:83]
	global_store_short_d16_hi v229, v239, s[82:83] offset:192
	global_store_short v229, v240, s[82:83] offset:384
	global_store_short_d16_hi v229, v240, s[82:83] offset:576
	s_add_u32 s82, s82, 1536
	s_addc_u32 s83, s83, 0
	v_cvt_pk_bf16_f32 v237, v56, v57
	v_cvt_pk_bf16_f32 v238, v58, v59
	global_store_short v229, v237, s[82:83]
	global_store_short_d16_hi v229, v237, s[82:83] offset:192
	global_store_short v229, v238, s[82:83] offset:384
	global_store_short_d16_hi v229, v238, s[82:83] offset:576
	s_add_u32 s82, s82, 1536
	s_addc_u32 s83, s83, 0
	v_cvt_pk_bf16_f32 v239, v60, v61
	v_cvt_pk_bf16_f32 v240, v62, v63
	global_store_short v229, v239, s[82:83]
	global_store_short_d16_hi v229, v239, s[82:83] offset:192
	global_store_short v229, v240, s[82:83] offset:384
	global_store_short_d16_hi v229, v240, s[82:83] offset:576
	s_add_u32 s82, s82, 1536
	s_addc_u32 s83, s83, 0
	v_cvt_pk_bf16_f32 v237, v80, v81
	v_cvt_pk_bf16_f32 v238, v82, v83
	global_store_short v229, v237, s[82:83]
	global_store_short_d16_hi v229, v237, s[82:83] offset:192
	global_store_short v229, v238, s[82:83] offset:384
	global_store_short_d16_hi v229, v238, s[82:83] offset:576
	s_add_u32 s82, s82, 1536
	s_addc_u32 s83, s83, 0
	v_cvt_pk_bf16_f32 v239, v84, v85
	v_cvt_pk_bf16_f32 v240, v86, v87
	global_store_short v229, v239, s[82:83]
	global_store_short_d16_hi v229, v239, s[82:83] offset:192
	global_store_short v229, v240, s[82:83] offset:384
	global_store_short_d16_hi v229, v240, s[82:83] offset:576
	s_add_u32 s82, s82, 1536
	s_addc_u32 s83, s83, 0
	v_cvt_pk_bf16_f32 v237, v88, v89
	v_cvt_pk_bf16_f32 v238, v90, v91
	global_store_short v229, v237, s[82:83]
	global_store_short_d16_hi v229, v237, s[82:83] offset:192
	global_store_short v229, v238, s[82:83] offset:384
	global_store_short_d16_hi v229, v238, s[82:83] offset:576
	s_add_u32 s82, s82, 1536
	s_addc_u32 s83, s83, 0
	v_cvt_pk_bf16_f32 v239, v92, v93
	v_cvt_pk_bf16_f32 v240, v94, v95
	global_store_short v229, v239, s[82:83]
	global_store_short_d16_hi v229, v239, s[82:83] offset:192
	global_store_short v229, v240, s[82:83] offset:384
	global_store_short_d16_hi v229, v240, s[82:83] offset:576
	s_add_u32 s82, s82, 1536
	s_addc_u32 s83, s83, 0
	v_cvt_pk_bf16_f32 v237, v112, v113
	v_cvt_pk_bf16_f32 v238, v114, v115
	global_store_short v229, v237, s[82:83]
	global_store_short_d16_hi v229, v237, s[82:83] offset:192
	global_store_short v229, v238, s[82:83] offset:384
	global_store_short_d16_hi v229, v238, s[82:83] offset:576
	s_add_u32 s82, s82, 1536
	s_addc_u32 s83, s83, 0
	v_cvt_pk_bf16_f32 v239, v116, v117
	v_cvt_pk_bf16_f32 v240, v118, v119
	global_store_short v229, v239, s[82:83]
	global_store_short_d16_hi v229, v239, s[82:83] offset:192
	global_store_short v229, v240, s[82:83] offset:384
	global_store_short_d16_hi v229, v240, s[82:83] offset:576
	s_add_u32 s82, s82, 1536
	s_addc_u32 s83, s83, 0
	v_cvt_pk_bf16_f32 v237, v120, v121
	v_cvt_pk_bf16_f32 v238, v122, v123
	global_store_short v229, v237, s[82:83]
	global_store_short_d16_hi v229, v237, s[82:83] offset:192
	global_store_short v229, v238, s[82:83] offset:384
	global_store_short_d16_hi v229, v238, s[82:83] offset:576
	s_add_u32 s82, s82, 1536
	s_addc_u32 s83, s83, 0
	v_cvt_pk_bf16_f32 v239, v124, v125
	v_cvt_pk_bf16_f32 v240, v126, v127
	global_store_short v229, v239, s[82:83]
	global_store_short_d16_hi v229, v239, s[82:83] offset:192
	global_store_short v229, v240, s[82:83] offset:384
	global_store_short_d16_hi v229, v240, s[82:83] offset:576
	s_add_u32 s82, s82, 1536
	s_addc_u32 s83, s83, 0
	s_branch .Lmg_next
; DI unsigned pack2(float lo, float hi) { f32x2_t v = {lo, hi}; bf16x2_t r = __builtin_convertvector(v, bf16x2_t); return __builtin_bit_cast(unsigned, r); }
; template <int EPI>
; DI void epilogue(const Params& p, int layer, f32x16 (&acc)[2][2], int mrow0, int ncol0, int lane) {
;     ...
;         } else {
; #pragma unroll
;           for (int g = 0; g < 4; ++g) {
;             int row = mrow0 + mi * 32 + 8 * g + 4 * h;
;             int b, kp; row_info(row, b, kp);
;             uint2 w;
;             w.x = pack2(acc[mi][ni][4 * g], acc[mi][ni][4 * g + 1]);
;             w.y = pack2(acc[mi][ni][4 * g + 2], acc[mi][ni][4 * g + 3]);
;             *(uint2*)(Vmt + ((size_t)(b * 6 + head) * 64 + (part - 2) * 32 + c) * NKEY + kp) = w;
;           }
.Lmg_kvv_28:
	s_movk_i32 s10, 0x2200
	v_mul_lo_u32 v229, v227, s10
	v_lshl_add_u32 v229, v228, 3, v229
	s_mul_i32 s10, s0, 6
	s_add_u32 s10, s10, s29
	s_lshl_b32 s10, s10, 6
	s_mul_i32 s10, s10, 0x2200
	s_lshl_b32 s11, s1, 1
	s_add_u32 s10, s10, s11
	s_add_u32 s10, s10, 0xf680000
	s_add_u32 s82, s24, s10
	s_addc_u32 s83, s25, 0
	v_cvt_pk_bf16_f32 v144, v0, v1
	v_cvt_pk_bf16_f32 v145, v2, v3
	global_store_dwordx2 v229, v[144:145], s[82:83]
	v_cvt_pk_bf16_f32 v146, v4, v5
	v_cvt_pk_bf16_f32 v147, v6, v7
	global_store_dwordx2 v229, v[146:147], s[82:83] offset:16
	v_cvt_pk_bf16_f32 v148, v8, v9
	v_cvt_pk_bf16_f32 v149, v10, v11
	global_store_dwordx2 v229, v[148:149], s[82:83] offset:32
	v_cvt_pk_bf16_f32 v150, v12, v13
	v_cvt_pk_bf16_f32 v151, v14, v15
	global_store_dwordx2 v229, v[150:151], s[82:83] offset:48
	v_cvt_pk_bf16_f32 v152, v32, v33
	v_cvt_pk_bf16_f32 v153, v34, v35
	global_store_dwordx2 v229, v[152:153], s[82:83] offset:64
	v_cvt_pk_bf16_f32 v154, v36, v37
	v_cvt_pk_bf16_f32 v155, v38, v39
	global_store_dwordx2 v229, v[154:155], s[82:83] offset:80
	v_cvt_pk_bf16_f32 v156, v40, v41
	v_cvt_pk_bf16_f32 v157, v42, v43
	global_store_dwordx2 v229, v[156:157], s[82:83] offset:96
	v_cvt_pk_bf16_f32 v158, v44, v45
	v_cvt_pk_bf16_f32 v159, v46, v47
	global_store_dwordx2 v229, v[158:159], s[82:83] offset:112
	v_cvt_pk_bf16_f32 v144, v64, v65
	v_cvt_pk_bf16_f32 v145, v66, v67
	global_store_dwordx2 v229, v[144:145], s[82:83] offset:128
	v_cvt_pk_bf16_f32 v146, v68, v69
	v_cvt_pk_bf16_f32 v147, v70, v71
	global_store_dwordx2 v229, v[146:147], s[82:83] offset:144
	v_cvt_pk_bf16_f32 v148, v72, v73
	v_cvt_pk_bf16_f32 v149, v74, v75
	global_store_dwordx2 v229, v[148:149], s[82:83] offset:160
	v_cvt_pk_bf16_f32 v150, v76, v77
	v_cvt_pk_bf16_f32 v151, v78, v79
	global_store_dwordx2 v229, v[150:151], s[82:83] offset:176
	v_cvt_pk_bf16_f32 v152, v96, v97
	v_cvt_pk_bf16_f32 v153, v98, v99
	global_store_dwordx2 v229, v[152:153], s[82:83] offset:192
	v_cvt_pk_bf16_f32 v154, v100, v101
	v_cvt_pk_bf16_f32 v155, v102, v103
	global_store_dwordx2 v229, v[154:155], s[82:83] offset:208
	v_cvt_pk_bf16_f32 v156, v104, v105
	v_cvt_pk_bf16_f32 v157, v106, v107
	global_store_dwordx2 v229, v[156:157], s[82:83] offset:224
	v_cvt_pk_bf16_f32 v158, v108, v109
	v_cvt_pk_bf16_f32 v159, v110, v111
	global_store_dwordx2 v229, v[158:159], s[82:83] offset:240
	s_mul_i32 s10, s0, 6
	s_add_u32 s10, s10, s29
	s_lshl_b32 s10, s10, 6
	s_add_u32 s10, s10, 32
	s_mul_i32 s10, s10, 0x2200
	s_lshl_b32 s11, s1, 1
	s_add_u32 s10, s10, s11
	s_add_u32 s10, s10, 0xf680000
	s_add_u32 s82, s24, s10
	s_addc_u32 s83, s25, 0
	v_cvt_pk_bf16_f32 v144, v16, v17
	v_cvt_pk_bf16_f32 v145, v18, v19
	global_store_dwordx2 v229, v[144:145], s[82:83]
	v_cvt_pk_bf16_f32 v146, v20, v21
	v_cvt_pk_bf16_f32 v147, v22, v23
	global_store_dwordx2 v229, v[146:147], s[82:83] offset:16
	v_cvt_pk_bf16_f32 v148, v24, v25
	v_cvt_pk_bf16_f32 v149, v26, v27
	global_store_dwordx2 v229, v[148:149], s[82:83] offset:32
	v_cvt_pk_bf16_f32 v150, v28, v29
	v_cvt_pk_bf16_f32 v151, v30, v31
	global_store_dwordx2 v229, v[150:151], s[82:83] offset:48
	v_cvt_pk_bf16_f32 v152, v48, v49
	v_cvt_pk_bf16_f32 v153, v50, v51
	global_store_dwordx2 v229, v[152:153], s[82:83] offset:64
	v_cvt_pk_bf16_f32 v154, v52, v53
	v_cvt_pk_bf16_f32 v155, v54, v55
	global_store_dwordx2 v229, v[154:155], s[82:83] offset:80
	v_cvt_pk_bf16_f32 v156, v56, v57
	v_cvt_pk_bf16_f32 v157, v58, v59
	global_store_dwordx2 v229, v[156:157], s[82:83] offset:96
	v_cvt_pk_bf16_f32 v158, v60, v61
	v_cvt_pk_bf16_f32 v159, v62, v63
	global_store_dwordx2 v229, v[158:159], s[82:83] offset:112
	v_cvt_pk_bf16_f32 v144, v80, v81
	v_cvt_pk_bf16_f32 v145, v82, v83
	global_store_dwordx2 v229, v[144:145], s[82:83] offset:128
	v_cvt_pk_bf16_f32 v146, v84, v85
	v_cvt_pk_bf16_f32 v147, v86, v87
	global_store_dwordx2 v229, v[146:147], s[82:83] offset:144
	v_cvt_pk_bf16_f32 v148, v88, v89
	v_cvt_pk_bf16_f32 v149, v90, v91
	global_store_dwordx2 v229, v[148:149], s[82:83] offset:160
	v_cvt_pk_bf16_f32 v150, v92, v93
	v_cvt_pk_bf16_f32 v151, v94, v95
	global_store_dwordx2 v229, v[150:151], s[82:83] offset:176
	v_cvt_pk_bf16_f32 v152, v112, v113
	v_cvt_pk_bf16_f32 v153, v114, v115
	global_store_dwordx2 v229, v[152:153], s[82:83] offset:192
	v_cvt_pk_bf16_f32 v154, v116, v117
	v_cvt_pk_bf16_f32 v155, v118, v119
	global_store_dwordx2 v229, v[154:155], s[82:83] offset:208
	v_cvt_pk_bf16_f32 v156, v120, v121
	v_cvt_pk_bf16_f32 v157, v122, v123
	global_store_dwordx2 v229, v[156:157], s[82:83] offset:224
	v_cvt_pk_bf16_f32 v158, v124, v125
	v_cvt_pk_bf16_f32 v159, v126, v127
	global_store_dwordx2 v229, v[158:159], s[82:83] offset:240
	s_branch .Lmg_next

; DI void phase_mix_a(const Params& p, int layer, char* smem) {
;     ...
;   gemm_phase<EPI_QUP>(p, layer, (const bf16_t*)(p.ws + OFF_MQN), 256, wl + W_UQ, 256, 256, (layer == 0) ? MT : NLAT / 128, 5, smem);
;   gemm_phase<EPI_KVUP>(p, layer, (const bf16_t*)(p.ws + OFF_MKVN), 128, wl + W_UKV, 128, 128, MT, 6, smem, true);
.Lmg_done:
	s_setprio 0
	s_cmp_eq_u32 s52, 4
	s_cbranch_scc0 .Lmg_nochain_29
	s_mov_b32 s100, 5
	s_branch .Lmg_reenter
.Lmg_nochain_29:
	s_mov_b32 s100, s52
	v_readlane_b32 s52, v254, 0
	v_readlane_b32 s53, v254, 1
	v_readlane_b32 s54, v254, 2
	v_readlane_b32 s55, v254, 3
	v_readlane_b32 s56, v254, 4
	v_readlane_b32 s57, v254, 5
	v_readlane_b32 s58, v254, 6
	v_readlane_b32 s59, v254, 7
	v_readlane_b32 s60, v254, 8
	v_readlane_b32 s61, v254, 9
	v_readlane_b32 s62, v254, 10
	v_readlane_b32 s63, v254, 11
	v_readlane_b32 s64, v254, 12
	v_readlane_b32 s65, v254, 13
	v_readlane_b32 s66, v254, 14
	v_readlane_b32 s67, v254, 15
	v_readlane_b32 s68, v254, 16
	v_readlane_b32 s69, v254, 17
	v_readlane_b32 s70, v254, 18
	v_readlane_b32 s71, v254, 19
	v_readlane_b32 s72, v254, 20
	v_readlane_b32 s73, v254, 21
	v_readlane_b32 s74, v254, 22
	v_readlane_b32 s75, v254, 23
	v_readlane_b32 s76, v254, 24
	v_readlane_b32 s77, v254, 25
	v_readlane_b32 s78, v254, 26
	v_readlane_b32 s79, v254, 27
	v_readlane_b32 s80, v254, 28
	v_readlane_b32 s81, v254, 29
	v_readlane_b32 s82, v254, 30
	v_readlane_b32 s83, v254, 31
	v_readlane_b32 s84, v254, 32
	v_readlane_b32 s85, v254, 33
	v_readlane_b32 s86, v254, 34
	v_readlane_b32 s87, v254, 35
	v_readlane_b32 s88, v254, 36
	v_readlane_b32 s89, v254, 37
	v_readlane_b32 s90, v254, 38
	v_readlane_b32 s91, v254, 39
	s_nop 3
	s_cmp_eq_u32 s100, 1
	s_cbranch_scc1 .LBB0_1546
	s_cmp_eq_u32 s100, 2
	s_cbranch_scc1 .LBB0_1650
	s_cmp_eq_u32 s100, 3
	s_cbranch_scc1 .LBB0_1711
	s_cmp_eq_u32 s100, 5
	s_cbranch_scc1 .LBB0_1397
	s_branch .LBB0_458
